# SwiGLU epilogue (ffn_up L0+L1): rstd partial-sum loads prefetched into free fragment registers before the ALIGN barrier
# baseline (speedup 1.0000x reference)
.LBB0_439:
	s_lshl_b32 s100, s36, 8
	s_cmp_eq_u32 s50, 2
	s_cselect_b32 s101, 0x80, 0
	s_or_b32 s100, s100, s101
	v_add_u32_e32 v152, s100, v219
	v_lshlrev_b32_e32 v153, 7, v152
	v_mov_b32_e32 v155, 0
	v_add_u32_e32 v154, 0, v153
	v_lshl_add_u64 v[156:157], v[154:155], 0, v[204:205]
	global_load_dwordx4 v[160:163], v[156:157], off
	global_load_dwordx4 v[164:167], v[156:157], off offset:16
	v_add_u32_e32 v154, 0x800, v153
	v_lshl_add_u64 v[156:157], v[154:155], 0, v[204:205]
	global_load_dwordx4 v[168:171], v[156:157], off
	global_load_dwordx4 v[172:175], v[156:157], off offset:16
	v_add_u32_e32 v154, 0x1000, v153
	v_lshl_add_u64 v[156:157], v[154:155], 0, v[204:205]
	global_load_dwordx4 v[176:179], v[156:157], off
	global_load_dwordx4 v[180:183], v[156:157], off offset:16
	v_add_u32_e32 v154, 0x1800, v153
	v_lshl_add_u64 v[156:157], v[154:155], 0, v[204:205]
	global_load_dwordx4 v[184:187], v[156:157], off
	global_load_dwordx4 v[188:191], v[156:157], off offset:16
	v_add_u32_e32 v154, 0x4000, v153
	v_lshl_add_u64 v[156:157], v[154:155], 0, v[204:205]
	global_load_dwordx4 v[192:195], v[156:157], off
	s_and_b64 vcc, exec, s[18:19]
	s_cbranch_vccz .LBB0_441
	s_barrier
.LBB0_441:
	s_lshl_b32 s23, s36, 8
	s_cmp_eq_u32 s50, 2
	s_cselect_b32 s25, 0x80, 0
	s_or_b32 s23, s23, s25
	v_add_u32_e32 v132, s23, v219
	v_ashrrev_i32_e32 v133, 31, v132
	v_lshlrev_b64 v[2:3], 7, v[132:133]
	v_lshl_add_u64 v[2:3], v[204:205], 0, v[2:3]
	v_and_b32_e32 v133, 64, v225
	v_xor_b32_e32 v1, 16, v225
	v_mov_b32_e32 v145, v118
	v_mov_b32_e32 v118, v127
	v_add_u32_e32 v127, 64, v133
	v_cmp_lt_i32_e32 vcc, v1, v127
	v_mov_b32_e32 v144, v126
	v_xor_b32_e32 v148, 32, v225
	v_cndmask_b32_e32 v1, v225, v1, vcc
	v_lshlrev_b32_e32 v126, 2, v1
	v_cmp_lt_i32_e32 vcc, v148, v127
	v_mov_b32_e32 v142, v128
	v_mov_b32_e32 v143, v120
	v_mov_b32_e32 v120, v129
	v_mov_b32_e32 v128, v130
	v_mov_b32_e32 v129, v122
	v_mov_b32_e32 v122, v131
	v_mov_b32_e32 v130, v124
	v_mov_b32_e32 v131, v116
	v_mov_b32_e32 v116, v125
	v_lshl_or_b32 v2, s51, 7, v221
	v_mov_b64_e32 v[124:125], s[14:15]
	v_ashrrev_i32_e32 v3, 31, v2
	v_lshlrev_b64 v[2:3], 1, v[2:3]
	s_waitcnt vmcnt(7)
	v_mov_b64_e32 v[134:135], v[160:161]
	v_mov_b64_e32 v[136:137], v[162:163]
	v_mov_b64_e32 v[138:139], v[164:165]
	v_mov_b64_e32 v[140:141], v[166:167]
	global_load_dwordx4 v[160:163], v[156:157], off offset:16
	v_add_u32_e32 v154, 0x4800, v153
	v_lshl_add_u64 v[156:157], v[154:155], 0, v[204:205]
	global_load_dwordx4 v[164:167], v[156:157], off
	v_mov_b32_e32 v146, v134
	v_mov_b32_e32 v147, v138
	v_mov_b32_e32 v138, v135
	v_mov_b32_e32 v134, v136
	v_mov_b32_e32 v135, v140
	v_mov_b32_e32 v140, v137
	v_pk_add_f32 v[136:137], v[146:147], v[138:139]
	v_pk_add_f32 v[134:135], v[134:135], v[140:141]
	s_nop 0
	v_pk_add_f32 v[134:135], v[136:137], v[134:135]
	v_or_b32_e32 v136, 16, v132
	v_add_f32_e32 v1, 0, v134
	v_add_f32_e32 v133, v1, v135
	ds_bpermute_b32 v134, v126, v133
	v_cndmask_b32_e32 v1, v225, v148, vcc
	v_lshlrev_b32_e32 v1, 2, v1
	v_ashrrev_i32_e32 v137, 31, v136
	v_lshlrev_b64 v[138:139], 7, v[136:137]
	s_waitcnt lgkmcnt(0)
	v_add_f32_e32 v127, v133, v134
	ds_bpermute_b32 v133, v1, v127
	v_mad_i64_i32 v[134:135], s[46:47], v132, s72, v[124:125]
	v_lshl_add_u64 v[134:135], v[134:135], 0, v[2:3]
	v_lshl_add_u64 v[138:139], v[204:205], 0, v[138:139]
	s_waitcnt lgkmcnt(0)
	v_add_f32_e32 v127, v127, v133
	v_fmamk_f32 v127, v127, 0x3a000000, v226
	v_mul_f32_e32 v133, 0x4b800000, v127
	v_cmp_gt_f32_e32 vcc, s71, v127
	s_nop 1
	v_cndmask_b32_e32 v127, v127, v133, vcc
	v_rsq_f32_e32 v127, v127
	s_nop 0
	v_mul_f32_e32 v133, 0x45800000, v127
	v_cndmask_b32_e32 v140, v127, v133, vcc
	v_pk_mul_f32 v[118:119], v[118:119], v[140:141] op_sel_hi:[1,0]
	v_pk_mul_f32 v[142:143], v[142:143], v[140:141] op_sel_hi:[1,0]
	v_pk_mul_f32 v[120:121], v[120:121], v[140:141] op_sel_hi:[1,0]
	v_pk_mul_f32 v[128:129], v[128:129], v[140:141] op_sel_hi:[1,0]
	v_pk_mul_f32 v[122:123], v[122:123], v[140:141] op_sel_hi:[1,0]
	v_pk_mul_f32 v[130:131], v[130:131], v[140:141] op_sel_hi:[1,0]
	v_pk_mul_f32 v[116:117], v[116:117], v[140:141] op_sel_hi:[1,0]
	v_pk_mul_f32 v[144:145], v[144:145], v[140:141] op_sel_hi:[1,0]
	v_mul_f32_e32 v148, 0xbfb8aa3b, v119
	v_mul_f32_e32 v127, 0xbfb8aa3b, v143
	v_mul_f32_e32 v133, 0xbfb8aa3b, v121
	v_mul_f32_e32 v137, 0xbfb8aa3b, v129
	v_mul_f32_e32 v140, 0xbfb8aa3b, v123
	v_mul_f32_e32 v141, 0xbfb8aa3b, v131
	v_mul_f32_e32 v146, 0xbfb8aa3b, v117
	v_mul_f32_e32 v147, 0xbfb8aa3b, v145
	v_exp_f32_e32 v148, v148
	v_exp_f32_e32 v127, v127
	v_exp_f32_e32 v133, v133
	v_exp_f32_e32 v137, v137
	v_exp_f32_e32 v140, v140
	v_exp_f32_e32 v141, v141
	v_exp_f32_e32 v146, v146
	v_exp_f32_e32 v147, v147
	v_add_f32_e32 v148, 1.0, v148
	v_add_f32_e32 v127, 1.0, v127
	v_add_f32_e32 v133, 1.0, v133
	v_add_f32_e32 v137, 1.0, v137
	v_add_f32_e32 v140, 1.0, v140
	v_add_f32_e32 v141, 1.0, v141
	v_add_f32_e32 v146, 1.0, v146
	v_add_f32_e32 v147, 1.0, v147
	v_rcp_f32_e32 v148, v148
	v_rcp_f32_e32 v127, v127
	v_rcp_f32_e32 v133, v133
	v_rcp_f32_e32 v137, v137
	v_rcp_f32_e32 v140, v140
	v_rcp_f32_e32 v141, v141
	v_rcp_f32_e32 v146, v146
	v_rcp_f32_e32 v147, v147
	v_mul_f32_e32 v119, v119, v148
	v_mul_f32_e32 v127, v143, v127
	v_mul_f32_e32 v121, v121, v133
	v_mul_f32_e32 v129, v129, v137
	v_mul_f32_e32 v123, v123, v140
	v_mul_f32_e32 v131, v131, v141
	v_mul_f32_e32 v117, v117, v146
	v_mul_f32_e32 v133, v145, v147
	v_mul_f32_e32 v119, v118, v119
	v_mul_f32_e32 v127, v142, v127
	v_mul_f32_e32 v120, v120, v121
	v_mul_f32_e32 v121, v128, v129
	v_mul_f32_e32 v122, v122, v123
	v_mul_f32_e32 v123, v130, v131
	v_mul_f32_e32 v128, v116, v117
	v_mul_f32_e32 v129, v144, v133
	v_cvt_pk_bf16_f32 v116, v127, v120
	v_cvt_pk_bf16_f32 v117, v121, v122
	v_cvt_pk_bf16_f32 v118, v123, v128
	v_cvt_pk_bf16_f32 v119, v129, v119
	global_store_dwordx4 v[134:135], v[116:119], off
	v_mov_b32_e32 v129, v104
	v_mov_b32_e32 v104, v113
	v_mov_b32_e32 v113, v106
	v_mov_b32_e32 v106, v115
	v_mov_b32_e32 v115, v100
	v_mov_b32_e32 v128, v112
	v_mov_b32_e32 v112, v114
	v_mov_b32_e32 v114, v108
	v_mov_b32_e32 v108, v110
	v_or_b32_e32 v110, 32, v132
	s_waitcnt vmcnt(9)
	v_mov_b64_e32 v[116:117], v[168:169]
	v_mov_b64_e32 v[118:119], v[170:171]
	global_load_dwordx4 v[168:171], v[156:157], off offset:16
	v_mov_b32_e32 v130, v116
	s_waitcnt vmcnt(9)
	v_mov_b64_e32 v[120:121], v[172:173]
	v_mov_b64_e32 v[122:123], v[174:175]
	v_add_u32_e32 v154, 0x5000, v153
	v_lshl_add_u64 v[156:157], v[154:155], 0, v[204:205]
	global_load_dwordx4 v[172:175], v[156:157], off
	v_mov_b32_e32 v131, v120
	v_mov_b32_e32 v120, v117
	v_mov_b32_e32 v116, v118
	v_mov_b32_e32 v117, v122
	v_mov_b32_e32 v122, v119
	v_pk_add_f32 v[118:119], v[130:131], v[120:121]
	v_pk_add_f32 v[116:117], v[116:117], v[122:123]
	s_nop 0
	v_pk_add_f32 v[116:117], v[118:119], v[116:117]
	s_nop 0
	v_add_f32_e32 v100, 0, v116
	v_add_f32_e32 v116, v100, v117
	ds_bpermute_b32 v117, v126, v116
	v_mov_b32_e32 v100, v109
	v_mov_b32_e32 v109, v102
	v_mov_b32_e32 v102, v111
	v_ashrrev_i32_e32 v111, 31, v110
	s_waitcnt lgkmcnt(0)
	v_add_f32_e32 v118, v116, v117
	ds_bpermute_b32 v119, v1, v118
	v_mad_i64_i32 v[116:117], s[46:47], v136, s72, v[124:125]
	v_lshl_add_u64 v[116:117], v[116:117], 0, v[2:3]
	s_waitcnt lgkmcnt(0)
	v_add_f32_e32 v118, v118, v119
	v_fmamk_f32 v118, v118, 0x3a000000, v226
	v_mul_f32_e32 v119, 0x4b800000, v118
	v_cmp_gt_f32_e32 vcc, s71, v118
	s_nop 1
	v_cndmask_b32_e32 v118, v118, v119, vcc
	v_rsq_f32_e32 v120, v118
	v_lshlrev_b64 v[118:119], 7, v[110:111]
	v_lshl_add_u64 v[118:119], v[204:205], 0, v[118:119]
	v_mul_f32_e32 v111, 0x45800000, v120
	v_cndmask_b32_e32 v120, v120, v111, vcc
	v_pk_mul_f32 v[102:103], v[102:103], v[120:121] op_sel_hi:[1,0]
	v_pk_mul_f32 v[122:123], v[128:129], v[120:121] op_sel_hi:[1,0]
	v_pk_mul_f32 v[104:105], v[104:105], v[120:121] op_sel_hi:[1,0]
	v_pk_mul_f32 v[112:113], v[112:113], v[120:121] op_sel_hi:[1,0]
	v_pk_mul_f32 v[106:107], v[106:107], v[120:121] op_sel_hi:[1,0]
	v_pk_mul_f32 v[114:115], v[114:115], v[120:121] op_sel_hi:[1,0]
	v_pk_mul_f32 v[100:101], v[100:101], v[120:121] op_sel_hi:[1,0]
	v_pk_mul_f32 v[108:109], v[108:109], v[120:121] op_sel_hi:[1,0]
	v_mul_f32_e32 v131, 0xbfb8aa3b, v103
	v_mul_f32_e32 v111, 0xbfb8aa3b, v123
	v_mul_f32_e32 v120, 0xbfb8aa3b, v105
	v_mul_f32_e32 v121, 0xbfb8aa3b, v113
	v_mul_f32_e32 v127, 0xbfb8aa3b, v107
	v_mul_f32_e32 v128, 0xbfb8aa3b, v115
	v_mul_f32_e32 v129, 0xbfb8aa3b, v101
	v_mul_f32_e32 v130, 0xbfb8aa3b, v109
	v_exp_f32_e32 v131, v131
	v_exp_f32_e32 v111, v111
	v_exp_f32_e32 v120, v120
	v_exp_f32_e32 v121, v121
	v_exp_f32_e32 v127, v127
	v_exp_f32_e32 v128, v128
	v_exp_f32_e32 v129, v129
	v_exp_f32_e32 v130, v130
	v_add_f32_e32 v131, 1.0, v131
	v_add_f32_e32 v111, 1.0, v111
	v_add_f32_e32 v120, 1.0, v120
	v_add_f32_e32 v121, 1.0, v121
	v_add_f32_e32 v127, 1.0, v127
	v_add_f32_e32 v128, 1.0, v128
	v_add_f32_e32 v129, 1.0, v129
	v_add_f32_e32 v130, 1.0, v130
	v_rcp_f32_e32 v131, v131
	v_rcp_f32_e32 v111, v111
	v_rcp_f32_e32 v120, v120
	v_rcp_f32_e32 v121, v121
	v_rcp_f32_e32 v127, v127
	v_rcp_f32_e32 v128, v128
	v_rcp_f32_e32 v129, v129
	v_rcp_f32_e32 v130, v130
	v_mul_f32_e32 v103, v103, v131
	v_mul_f32_e32 v111, v123, v111
	v_mul_f32_e32 v105, v105, v120
	v_mul_f32_e32 v113, v113, v121
	v_mul_f32_e32 v107, v107, v127
	v_mul_f32_e32 v115, v115, v128
	v_mul_f32_e32 v101, v101, v129
	v_mul_f32_e32 v109, v109, v130
	v_mul_f32_e32 v103, v102, v103
	v_mul_f32_e32 v111, v122, v111
	v_mul_f32_e32 v104, v104, v105
	v_mul_f32_e32 v105, v112, v113
	v_mul_f32_e32 v106, v106, v107
	v_mul_f32_e32 v107, v114, v115
	v_mul_f32_e32 v112, v100, v101
	v_mul_f32_e32 v108, v108, v109
	v_cvt_pk_bf16_f32 v100, v111, v104
	v_cvt_pk_bf16_f32 v101, v105, v106
	v_cvt_pk_bf16_f32 v102, v107, v112
	v_cvt_pk_bf16_f32 v103, v108, v103
	global_store_dwordx4 v[116:117], v[100:103], off
	v_mov_b32_e32 v109, v88
	v_mov_b32_e32 v88, v97
	v_mov_b32_e32 v97, v90
	v_mov_b32_e32 v90, v99
	v_mov_b32_e32 v99, v84
	v_mov_b32_e32 v108, v96
	v_mov_b32_e32 v96, v98
	v_mov_b32_e32 v98, v92
	v_mov_b32_e32 v92, v94
	v_or_b32_e32 v94, 48, v132
	s_waitcnt vmcnt(10)
	v_mov_b64_e32 v[100:101], v[176:177]
	v_mov_b64_e32 v[102:103], v[178:179]
	global_load_dwordx4 v[176:179], v[156:157], off offset:16
	v_mov_b32_e32 v112, v100
	s_waitcnt vmcnt(10)
	v_mov_b64_e32 v[104:105], v[180:181]
	v_mov_b64_e32 v[106:107], v[182:183]
	v_add_u32_e32 v154, 0x5800, v153
	v_lshl_add_u64 v[156:157], v[154:155], 0, v[204:205]
	global_load_dwordx4 v[180:183], v[156:157], off
	v_mov_b32_e32 v113, v104
	v_mov_b32_e32 v104, v101
	v_mov_b32_e32 v100, v102
	v_mov_b32_e32 v101, v106
	v_mov_b32_e32 v106, v103
	v_pk_add_f32 v[102:103], v[112:113], v[104:105]
	v_pk_add_f32 v[100:101], v[100:101], v[106:107]
	s_nop 0
	v_pk_add_f32 v[100:101], v[102:103], v[100:101]
	s_nop 0
	v_add_f32_e32 v84, 0, v100
	v_add_f32_e32 v100, v84, v101
	ds_bpermute_b32 v101, v126, v100
	v_mov_b32_e32 v84, v93
	v_mov_b32_e32 v93, v86
	v_mov_b32_e32 v86, v95
	v_ashrrev_i32_e32 v95, 31, v94
	s_waitcnt lgkmcnt(0)
	v_add_f32_e32 v102, v100, v101
	ds_bpermute_b32 v103, v1, v102
	v_mad_i64_i32 v[100:101], s[46:47], v110, s72, v[124:125]
	v_lshl_add_u64 v[100:101], v[100:101], 0, v[2:3]
	s_waitcnt lgkmcnt(0)
	v_add_f32_e32 v102, v102, v103
	v_fmamk_f32 v102, v102, 0x3a000000, v226
	v_mul_f32_e32 v103, 0x4b800000, v102
	v_cmp_gt_f32_e32 vcc, s71, v102
	s_nop 1
	v_cndmask_b32_e32 v102, v102, v103, vcc
	v_rsq_f32_e32 v104, v102
	v_lshlrev_b64 v[102:103], 7, v[94:95]
	v_lshl_add_u64 v[102:103], v[204:205], 0, v[102:103]
	v_mul_f32_e32 v95, 0x45800000, v104
	v_cndmask_b32_e32 v104, v104, v95, vcc
	v_pk_mul_f32 v[86:87], v[86:87], v[104:105] op_sel_hi:[1,0]
	v_pk_mul_f32 v[106:107], v[108:109], v[104:105] op_sel_hi:[1,0]
	v_pk_mul_f32 v[88:89], v[88:89], v[104:105] op_sel_hi:[1,0]
	v_pk_mul_f32 v[96:97], v[96:97], v[104:105] op_sel_hi:[1,0]
	v_pk_mul_f32 v[90:91], v[90:91], v[104:105] op_sel_hi:[1,0]
	v_pk_mul_f32 v[98:99], v[98:99], v[104:105] op_sel_hi:[1,0]
	v_pk_mul_f32 v[84:85], v[84:85], v[104:105] op_sel_hi:[1,0]
	v_pk_mul_f32 v[92:93], v[92:93], v[104:105] op_sel_hi:[1,0]
	v_mul_f32_e32 v112, 0xbfb8aa3b, v87
	v_mul_f32_e32 v95, 0xbfb8aa3b, v107
	v_mul_f32_e32 v104, 0xbfb8aa3b, v89
	v_mul_f32_e32 v105, 0xbfb8aa3b, v97
	v_mul_f32_e32 v108, 0xbfb8aa3b, v91
	v_mul_f32_e32 v109, 0xbfb8aa3b, v99
	v_mul_f32_e32 v110, 0xbfb8aa3b, v85
	v_mul_f32_e32 v111, 0xbfb8aa3b, v93
	v_exp_f32_e32 v112, v112
	v_exp_f32_e32 v95, v95
	v_exp_f32_e32 v104, v104
	v_exp_f32_e32 v105, v105
	v_exp_f32_e32 v108, v108
	v_exp_f32_e32 v109, v109
	v_exp_f32_e32 v110, v110
	v_exp_f32_e32 v111, v111
	v_add_f32_e32 v112, 1.0, v112
	v_add_f32_e32 v95, 1.0, v95
	v_add_f32_e32 v104, 1.0, v104
	v_add_f32_e32 v105, 1.0, v105
	v_add_f32_e32 v108, 1.0, v108
	v_add_f32_e32 v109, 1.0, v109
	v_add_f32_e32 v110, 1.0, v110
	v_add_f32_e32 v111, 1.0, v111
	v_rcp_f32_e32 v112, v112
	v_rcp_f32_e32 v95, v95
	v_rcp_f32_e32 v104, v104
	v_rcp_f32_e32 v105, v105
	v_rcp_f32_e32 v108, v108
	v_rcp_f32_e32 v109, v109
	v_rcp_f32_e32 v110, v110
	v_rcp_f32_e32 v111, v111
	v_mul_f32_e32 v87, v87, v112
	v_mul_f32_e32 v95, v107, v95
	v_mul_f32_e32 v89, v89, v104
	v_mul_f32_e32 v97, v97, v105
	v_mul_f32_e32 v91, v91, v108
	v_mul_f32_e32 v99, v99, v109
	v_mul_f32_e32 v85, v85, v110
	v_mul_f32_e32 v93, v93, v111
	v_mul_f32_e32 v87, v86, v87
	v_mul_f32_e32 v95, v106, v95
	v_mul_f32_e32 v88, v88, v89
	v_mul_f32_e32 v89, v96, v97
	v_mul_f32_e32 v90, v90, v91
	v_mul_f32_e32 v91, v98, v99
	v_mul_f32_e32 v96, v84, v85
	v_mul_f32_e32 v92, v92, v93
	v_cvt_pk_bf16_f32 v84, v95, v88
	v_cvt_pk_bf16_f32 v85, v89, v90
	v_cvt_pk_bf16_f32 v86, v91, v96
	v_cvt_pk_bf16_f32 v87, v92, v87
	global_store_dwordx4 v[100:101], v[84:87], off
	v_mov_b32_e32 v93, v76
	v_mov_b32_e32 v76, v81
	v_mov_b32_e32 v92, v80
	v_mov_b32_e32 v80, v82
	v_mov_b32_e32 v82, v68
	v_mov_b32_e32 v68, v70
	s_waitcnt vmcnt(11)
	v_mov_b64_e32 v[84:85], v[184:185]
	v_mov_b64_e32 v[86:87], v[186:187]
	global_load_dwordx4 v[184:187], v[156:157], off offset:16
	v_mov_b32_e32 v96, v84
	s_waitcnt vmcnt(11)
	v_mov_b64_e32 v[88:89], v[188:189]
	v_mov_b64_e32 v[90:91], v[190:191]
	v_mov_b32_e32 v97, v88
	v_mov_b32_e32 v88, v85
	v_mov_b32_e32 v84, v86
	v_mov_b32_e32 v85, v90
	v_mov_b32_e32 v90, v87
	v_pk_add_f32 v[86:87], v[96:97], v[88:89]
	v_pk_add_f32 v[84:85], v[84:85], v[90:91]
	s_nop 0
	v_pk_add_f32 v[84:85], v[86:87], v[84:85]
	s_nop 0
	v_add_f32_e32 v81, 0, v84
	v_add_f32_e32 v84, v81, v85
	ds_bpermute_b32 v85, v126, v84
	v_mov_b32_e32 v81, v78
	v_mov_b32_e32 v78, v83
	v_mov_b32_e32 v83, v72
	v_mov_b32_e32 v72, v69
	s_waitcnt lgkmcnt(0)
	v_add_f32_e32 v84, v84, v85
	ds_bpermute_b32 v85, v1, v84
	v_mov_b32_e32 v69, v74
	v_mov_b32_e32 v74, v71
	s_waitcnt lgkmcnt(0)
	v_add_f32_e32 v70, v84, v85
	v_fmamk_f32 v70, v70, 0x3a000000, v226
	v_mul_f32_e32 v71, 0x4b800000, v70
	v_cmp_gt_f32_e32 vcc, s71, v70
	s_nop 1
	v_cndmask_b32_e32 v70, v70, v71, vcc
	v_rsq_f32_e32 v86, v70
	v_mad_i64_i32 v[70:71], s[46:47], v94, s72, v[124:125]
	v_lshl_add_u64 v[84:85], v[70:71], 0, v[2:3]
	v_mul_f32_e32 v70, 0x45800000, v86
	v_cndmask_b32_e32 v70, v86, v70, vcc
	v_pk_mul_f32 v[86:87], v[92:93], v[70:71] op_sel_hi:[1,0]
	v_pk_mul_f32 v[76:77], v[76:77], v[70:71] op_sel_hi:[1,0]
	v_pk_mul_f32 v[80:81], v[80:81], v[70:71] op_sel_hi:[1,0]
	v_pk_mul_f32 v[78:79], v[78:79], v[70:71] op_sel_hi:[1,0]
	v_pk_mul_f32 v[82:83], v[82:83], v[70:71] op_sel_hi:[1,0]
	v_pk_mul_f32 v[72:73], v[72:73], v[70:71] op_sel_hi:[1,0]
	v_pk_mul_f32 v[68:69], v[68:69], v[70:71] op_sel_hi:[1,0]
	v_pk_mul_f32 v[70:71], v[74:75], v[70:71] op_sel_hi:[1,0]
	v_mul_f32_e32 v74, 0xbfb8aa3b, v87
	v_mul_f32_e32 v93, 0xbfb8aa3b, v71
	v_mul_f32_e32 v75, 0xbfb8aa3b, v77
	v_mul_f32_e32 v88, 0xbfb8aa3b, v81
	v_mul_f32_e32 v89, 0xbfb8aa3b, v79
	v_mul_f32_e32 v90, 0xbfb8aa3b, v83
	v_mul_f32_e32 v91, 0xbfb8aa3b, v73
	v_mul_f32_e32 v92, 0xbfb8aa3b, v69
	v_exp_f32_e32 v93, v93
	v_exp_f32_e32 v74, v74
	v_exp_f32_e32 v75, v75
	v_exp_f32_e32 v88, v88
	v_exp_f32_e32 v89, v89
	v_exp_f32_e32 v90, v90
	v_exp_f32_e32 v91, v91
	v_exp_f32_e32 v92, v92
	v_add_f32_e32 v93, 1.0, v93
	v_add_f32_e32 v74, 1.0, v74
	v_add_f32_e32 v75, 1.0, v75
	v_add_f32_e32 v88, 1.0, v88
	v_add_f32_e32 v89, 1.0, v89
	v_add_f32_e32 v90, 1.0, v90
	v_add_f32_e32 v91, 1.0, v91
	v_add_f32_e32 v92, 1.0, v92
	v_rcp_f32_e32 v93, v93
	v_rcp_f32_e32 v74, v74
	v_rcp_f32_e32 v75, v75
	v_rcp_f32_e32 v88, v88
	v_rcp_f32_e32 v89, v89
	v_rcp_f32_e32 v90, v90
	v_rcp_f32_e32 v91, v91
	v_rcp_f32_e32 v92, v92
	v_mul_f32_e32 v71, v71, v93
	v_mul_f32_e32 v74, v87, v74
	v_mul_f32_e32 v75, v77, v75
	v_mul_f32_e32 v77, v81, v88
	v_mul_f32_e32 v79, v79, v89
	v_mul_f32_e32 v81, v83, v90
	v_mul_f32_e32 v73, v73, v91
	v_mul_f32_e32 v69, v69, v92
	v_mul_f32_e32 v71, v70, v71
	v_mul_f32_e32 v74, v86, v74
	v_mul_f32_e32 v75, v76, v75
	v_mul_f32_e32 v76, v80, v77
	v_mul_f32_e32 v77, v78, v79
	v_mul_f32_e32 v78, v82, v81
	v_mul_f32_e32 v72, v72, v73
	v_mul_f32_e32 v73, v68, v69
	v_cvt_pk_bf16_f32 v68, v74, v75
	v_cvt_pk_bf16_f32 v69, v76, v77
	v_cvt_pk_bf16_f32 v70, v78, v72
	v_cvt_pk_bf16_f32 v71, v73, v71
	global_store_dwordx4 v[84:85], v[68:71], off
	s_and_b64 vcc, exec, s[10:11]
	s_cbranch_vccz .LBB0_443
	s_waitcnt vmcnt(0)
	s_andn2_b64 vcc, exec, s[26:27]
	s_mov_b64 s[10:11], -1
	s_cbranch_vccnz .LBB0_422
	s_branch .LBB0_444
.LBB0_443:
	v_add_u32_e32 v76, 0x80, v132
	v_ashrrev_i32_e32 v77, 31, v76
	v_lshlrev_b64 v[68:69], 7, v[76:77]
	v_lshl_add_u64 v[72:73], v[204:205], 0, v[68:69]
	s_nop 0
	v_mov_b32_e32 v78, v64
	v_mov_b32_e32 v79, v56
	v_mov_b32_e32 v56, v65
	v_mov_b32_e32 v64, v66
	v_mov_b32_e32 v65, v58
	v_mov_b32_e32 v58, v67
	v_mov_b32_e32 v66, v60
	v_mov_b32_e32 v67, v52
	v_mov_b32_e32 v52, v61
	s_waitcnt vmcnt(11)
	v_mov_b64_e32 v[68:69], v[192:193]
	v_mov_b64_e32 v[70:71], v[194:195]
	v_mov_b32_e32 v60, v68
	s_waitcnt vmcnt(10)
	v_mov_b64_e32 v[72:73], v[160:161]
	v_mov_b64_e32 v[74:75], v[162:163]
	v_mov_b32_e32 v61, v72
	v_mov_b32_e32 v72, v69
	v_mov_b32_e32 v68, v70
	v_mov_b32_e32 v69, v74
	v_mov_b32_e32 v74, v71
	v_pk_add_f32 v[60:61], v[60:61], v[72:73]
	v_pk_add_f32 v[68:69], v[68:69], v[74:75]
	s_nop 0
	v_pk_add_f32 v[60:61], v[60:61], v[68:69]
	v_mov_b32_e32 v68, v62
	v_add_f32_e32 v60, 0, v60
	v_add_f32_e32 v70, v60, v61
	ds_bpermute_b32 v71, v126, v70
	v_add_u32_e32 v62, 0x90, v132
	v_mov_b32_e32 v69, v54
	v_mov_b32_e32 v54, v63
	v_ashrrev_i32_e32 v63, 31, v62
	s_waitcnt lgkmcnt(0)
	v_add_f32_e32 v72, v70, v71
	ds_bpermute_b32 v73, v1, v72
	v_mov_b64_e32 v[60:61], s[14:15]
	v_mad_i64_i32 v[70:71], s[10:11], v76, s72, v[60:61]
	v_lshl_add_u64 v[70:71], v[70:71], 0, v[2:3]
	s_waitcnt lgkmcnt(0)
	v_add_f32_e32 v72, v72, v73
	v_fmamk_f32 v72, v72, 0x3a000000, v226
	v_mul_f32_e32 v73, 0x4b800000, v72
	v_cmp_gt_f32_e32 vcc, s71, v72
	s_nop 1
	v_cndmask_b32_e32 v72, v72, v73, vcc
	v_rsq_f32_e32 v74, v72
	v_lshlrev_b64 v[72:73], 7, v[62:63]
	v_lshl_add_u64 v[72:73], v[204:205], 0, v[72:73]
	v_mul_f32_e32 v63, 0x45800000, v74
	v_cndmask_b32_e32 v74, v74, v63, vcc
	v_pk_mul_f32 v[54:55], v[54:55], v[74:75] op_sel_hi:[1,0]
	v_pk_mul_f32 v[76:77], v[78:79], v[74:75] op_sel_hi:[1,0]
	v_pk_mul_f32 v[56:57], v[56:57], v[74:75] op_sel_hi:[1,0]
	v_pk_mul_f32 v[64:65], v[64:65], v[74:75] op_sel_hi:[1,0]
	v_pk_mul_f32 v[58:59], v[58:59], v[74:75] op_sel_hi:[1,0]
	v_pk_mul_f32 v[66:67], v[66:67], v[74:75] op_sel_hi:[1,0]
	v_pk_mul_f32 v[52:53], v[52:53], v[74:75] op_sel_hi:[1,0]
	v_pk_mul_f32 v[68:69], v[68:69], v[74:75] op_sel_hi:[1,0]
	v_mul_f32_e32 v82, 0xbfb8aa3b, v55
	v_mul_f32_e32 v63, 0xbfb8aa3b, v77
	v_mul_f32_e32 v74, 0xbfb8aa3b, v57
	v_mul_f32_e32 v75, 0xbfb8aa3b, v65
	v_mul_f32_e32 v78, 0xbfb8aa3b, v59
	v_mul_f32_e32 v79, 0xbfb8aa3b, v67
	v_mul_f32_e32 v80, 0xbfb8aa3b, v53
	v_mul_f32_e32 v81, 0xbfb8aa3b, v69
	v_exp_f32_e32 v82, v82
	v_exp_f32_e32 v63, v63
	v_exp_f32_e32 v74, v74
	v_exp_f32_e32 v75, v75
	v_exp_f32_e32 v78, v78
	v_exp_f32_e32 v79, v79
	v_exp_f32_e32 v80, v80
	v_exp_f32_e32 v81, v81
	v_add_f32_e32 v82, 1.0, v82
	v_add_f32_e32 v63, 1.0, v63
	v_add_f32_e32 v74, 1.0, v74
	v_add_f32_e32 v75, 1.0, v75
	v_add_f32_e32 v78, 1.0, v78
	v_add_f32_e32 v79, 1.0, v79
	v_add_f32_e32 v80, 1.0, v80
	v_add_f32_e32 v81, 1.0, v81
	v_rcp_f32_e32 v82, v82
	v_rcp_f32_e32 v63, v63
	v_rcp_f32_e32 v74, v74
	v_rcp_f32_e32 v75, v75
	v_rcp_f32_e32 v78, v78
	v_rcp_f32_e32 v79, v79
	v_rcp_f32_e32 v80, v80
	v_rcp_f32_e32 v81, v81
	v_mul_f32_e32 v55, v55, v82
	v_mul_f32_e32 v63, v77, v63
	v_mul_f32_e32 v57, v57, v74
	v_mul_f32_e32 v65, v65, v75
	v_mul_f32_e32 v59, v59, v78
	v_mul_f32_e32 v67, v67, v79
	v_mul_f32_e32 v53, v53, v80
	v_mul_f32_e32 v69, v69, v81
	v_mul_f32_e32 v55, v54, v55
	v_mul_f32_e32 v63, v76, v63
	v_mul_f32_e32 v56, v56, v57
	v_mul_f32_e32 v57, v64, v65
	v_mul_f32_e32 v58, v58, v59
	v_mul_f32_e32 v59, v66, v67
	v_mul_f32_e32 v64, v52, v53
	v_mul_f32_e32 v65, v68, v69
	v_cvt_pk_bf16_f32 v52, v63, v56
	v_cvt_pk_bf16_f32 v53, v57, v58
	v_cvt_pk_bf16_f32 v54, v59, v64
	v_cvt_pk_bf16_f32 v55, v65, v55
	global_store_dwordx4 v[70:71], v[52:55], off
	v_mov_b32_e32 v65, v40
	v_mov_b32_e32 v40, v49
	v_mov_b32_e32 v49, v42
	v_mov_b32_e32 v42, v51
	v_mov_b32_e32 v51, v36
	v_mov_b32_e32 v64, v48
	v_mov_b32_e32 v48, v50
	v_mov_b32_e32 v50, v44
	v_mov_b32_e32 v44, v46
	v_add_u32_e32 v46, 0xa0, v132
	s_waitcnt vmcnt(10)
	v_mov_b64_e32 v[52:53], v[164:165]
	v_mov_b64_e32 v[54:55], v[166:167]
	v_mov_b32_e32 v66, v52
	s_waitcnt vmcnt(8)
	v_mov_b64_e32 v[56:57], v[168:169]
	v_mov_b64_e32 v[58:59], v[170:171]
	v_mov_b32_e32 v67, v56
	v_mov_b32_e32 v56, v53
	v_mov_b32_e32 v52, v54
	v_mov_b32_e32 v53, v58
	v_mov_b32_e32 v58, v55
	v_pk_add_f32 v[54:55], v[66:67], v[56:57]
	v_pk_add_f32 v[52:53], v[52:53], v[58:59]
	s_nop 0
	v_pk_add_f32 v[52:53], v[54:55], v[52:53]
	s_nop 0
	v_add_f32_e32 v36, 0, v52
	v_add_f32_e32 v52, v36, v53
	ds_bpermute_b32 v53, v126, v52
	v_mov_b32_e32 v36, v45
	v_mov_b32_e32 v45, v38
	v_mov_b32_e32 v38, v47
	v_ashrrev_i32_e32 v47, 31, v46
	s_waitcnt lgkmcnt(0)
	v_add_f32_e32 v54, v52, v53
	ds_bpermute_b32 v55, v1, v54
	v_mad_i64_i32 v[52:53], s[10:11], v62, s72, v[60:61]
	v_lshl_add_u64 v[52:53], v[52:53], 0, v[2:3]
	s_waitcnt lgkmcnt(0)
	v_add_f32_e32 v54, v54, v55
	v_fmamk_f32 v54, v54, 0x3a000000, v226
	v_mul_f32_e32 v55, 0x4b800000, v54
	v_cmp_gt_f32_e32 vcc, s71, v54
	s_nop 1
	v_cndmask_b32_e32 v54, v54, v55, vcc
	v_rsq_f32_e32 v56, v54
	v_lshlrev_b64 v[54:55], 7, v[46:47]
	v_lshl_add_u64 v[54:55], v[204:205], 0, v[54:55]
	v_mul_f32_e32 v47, 0x45800000, v56
	v_cndmask_b32_e32 v56, v56, v47, vcc
	v_pk_mul_f32 v[38:39], v[38:39], v[56:57] op_sel_hi:[1,0]
	v_pk_mul_f32 v[58:59], v[64:65], v[56:57] op_sel_hi:[1,0]
	v_pk_mul_f32 v[40:41], v[40:41], v[56:57] op_sel_hi:[1,0]
	v_pk_mul_f32 v[48:49], v[48:49], v[56:57] op_sel_hi:[1,0]
	v_pk_mul_f32 v[42:43], v[42:43], v[56:57] op_sel_hi:[1,0]
	v_pk_mul_f32 v[50:51], v[50:51], v[56:57] op_sel_hi:[1,0]
	v_pk_mul_f32 v[36:37], v[36:37], v[56:57] op_sel_hi:[1,0]
	v_pk_mul_f32 v[44:45], v[44:45], v[56:57] op_sel_hi:[1,0]
	v_mul_f32_e32 v66, 0xbfb8aa3b, v39
	v_mul_f32_e32 v47, 0xbfb8aa3b, v59
	v_mul_f32_e32 v56, 0xbfb8aa3b, v41
	v_mul_f32_e32 v57, 0xbfb8aa3b, v49
	v_mul_f32_e32 v62, 0xbfb8aa3b, v43
	v_mul_f32_e32 v63, 0xbfb8aa3b, v51
	v_mul_f32_e32 v64, 0xbfb8aa3b, v37
	v_mul_f32_e32 v65, 0xbfb8aa3b, v45
	v_exp_f32_e32 v66, v66
	v_exp_f32_e32 v47, v47
	v_exp_f32_e32 v56, v56
	v_exp_f32_e32 v57, v57
	v_exp_f32_e32 v62, v62
	v_exp_f32_e32 v63, v63
	v_exp_f32_e32 v64, v64
	v_exp_f32_e32 v65, v65
	v_add_f32_e32 v66, 1.0, v66
	v_add_f32_e32 v47, 1.0, v47
	v_add_f32_e32 v56, 1.0, v56
	v_add_f32_e32 v57, 1.0, v57
	v_add_f32_e32 v62, 1.0, v62
	v_add_f32_e32 v63, 1.0, v63
	v_add_f32_e32 v64, 1.0, v64
	v_add_f32_e32 v65, 1.0, v65
	v_rcp_f32_e32 v66, v66
	v_rcp_f32_e32 v47, v47
	v_rcp_f32_e32 v56, v56
	v_rcp_f32_e32 v57, v57
	v_rcp_f32_e32 v62, v62
	v_rcp_f32_e32 v63, v63
	v_rcp_f32_e32 v64, v64
	v_rcp_f32_e32 v65, v65
	v_mul_f32_e32 v39, v39, v66
	v_mul_f32_e32 v47, v59, v47
	v_mul_f32_e32 v41, v41, v56
	v_mul_f32_e32 v49, v49, v57
	v_mul_f32_e32 v43, v43, v62
	v_mul_f32_e32 v51, v51, v63
	v_mul_f32_e32 v37, v37, v64
	v_mul_f32_e32 v45, v45, v65
	v_mul_f32_e32 v39, v38, v39
	v_mul_f32_e32 v47, v58, v47
	v_mul_f32_e32 v40, v40, v41
	v_mul_f32_e32 v41, v48, v49
	v_mul_f32_e32 v42, v42, v43
	v_mul_f32_e32 v43, v50, v51
	v_mul_f32_e32 v48, v36, v37
	v_mul_f32_e32 v44, v44, v45
	v_cvt_pk_bf16_f32 v36, v47, v40
	v_cvt_pk_bf16_f32 v37, v41, v42
	v_cvt_pk_bf16_f32 v38, v43, v48
	v_cvt_pk_bf16_f32 v39, v44, v39
	global_store_dwordx4 v[52:53], v[36:39], off
	v_mov_b32_e32 v45, v24
	v_mov_b32_e32 v24, v33
	v_mov_b32_e32 v33, v26
	v_mov_b32_e32 v26, v35
	v_mov_b32_e32 v35, v20
	v_mov_b32_e32 v44, v32
	v_mov_b32_e32 v32, v34
	v_mov_b32_e32 v34, v28
	v_mov_b32_e32 v28, v30
	v_add_u32_e32 v30, 0xb0, v132
	s_waitcnt vmcnt(8)
	v_mov_b64_e32 v[36:37], v[172:173]
	v_mov_b64_e32 v[38:39], v[174:175]
	v_mov_b32_e32 v48, v36
	s_waitcnt vmcnt(6)
	v_mov_b64_e32 v[40:41], v[176:177]
	v_mov_b64_e32 v[42:43], v[178:179]
	v_mov_b32_e32 v49, v40
	v_mov_b32_e32 v40, v37
	v_mov_b32_e32 v36, v38
	v_mov_b32_e32 v37, v42
	v_mov_b32_e32 v42, v39
	v_pk_add_f32 v[38:39], v[48:49], v[40:41]
	v_pk_add_f32 v[36:37], v[36:37], v[42:43]
	s_nop 0
	v_pk_add_f32 v[36:37], v[38:39], v[36:37]
	s_nop 0
	v_add_f32_e32 v20, 0, v36
	v_add_f32_e32 v36, v20, v37
	ds_bpermute_b32 v37, v126, v36
	v_mov_b32_e32 v20, v29
	v_mov_b32_e32 v29, v22
	v_mov_b32_e32 v22, v31
	v_ashrrev_i32_e32 v31, 31, v30
	s_waitcnt lgkmcnt(0)
	v_add_f32_e32 v38, v36, v37
	ds_bpermute_b32 v39, v1, v38
	v_mad_i64_i32 v[36:37], s[10:11], v46, s72, v[60:61]
	v_lshl_add_u64 v[36:37], v[36:37], 0, v[2:3]
	s_waitcnt lgkmcnt(0)
	v_add_f32_e32 v38, v38, v39
	v_fmamk_f32 v38, v38, 0x3a000000, v226
	v_mul_f32_e32 v39, 0x4b800000, v38
	v_cmp_gt_f32_e32 vcc, s71, v38
	s_nop 1
	v_cndmask_b32_e32 v38, v38, v39, vcc
	v_rsq_f32_e32 v40, v38
	v_lshlrev_b64 v[38:39], 7, v[30:31]
	v_lshl_add_u64 v[38:39], v[204:205], 0, v[38:39]
	v_mul_f32_e32 v31, 0x45800000, v40
	v_cndmask_b32_e32 v40, v40, v31, vcc
	v_pk_mul_f32 v[22:23], v[22:23], v[40:41] op_sel_hi:[1,0]
	v_pk_mul_f32 v[42:43], v[44:45], v[40:41] op_sel_hi:[1,0]
	v_pk_mul_f32 v[24:25], v[24:25], v[40:41] op_sel_hi:[1,0]
	v_pk_mul_f32 v[32:33], v[32:33], v[40:41] op_sel_hi:[1,0]
	v_pk_mul_f32 v[26:27], v[26:27], v[40:41] op_sel_hi:[1,0]
	v_pk_mul_f32 v[34:35], v[34:35], v[40:41] op_sel_hi:[1,0]
	v_pk_mul_f32 v[20:21], v[20:21], v[40:41] op_sel_hi:[1,0]
	v_pk_mul_f32 v[28:29], v[28:29], v[40:41] op_sel_hi:[1,0]
	v_mul_f32_e32 v48, 0xbfb8aa3b, v23
	v_mul_f32_e32 v31, 0xbfb8aa3b, v43
	v_mul_f32_e32 v40, 0xbfb8aa3b, v25
	v_mul_f32_e32 v41, 0xbfb8aa3b, v33
	v_mul_f32_e32 v44, 0xbfb8aa3b, v27
	v_mul_f32_e32 v45, 0xbfb8aa3b, v35
	v_mul_f32_e32 v46, 0xbfb8aa3b, v21
	v_mul_f32_e32 v47, 0xbfb8aa3b, v29
	v_exp_f32_e32 v48, v48
	v_exp_f32_e32 v31, v31
	v_exp_f32_e32 v40, v40
	v_exp_f32_e32 v41, v41
	v_exp_f32_e32 v44, v44
	v_exp_f32_e32 v45, v45
	v_exp_f32_e32 v46, v46
	v_exp_f32_e32 v47, v47
	v_add_f32_e32 v48, 1.0, v48
	v_add_f32_e32 v31, 1.0, v31
	v_add_f32_e32 v40, 1.0, v40
	v_add_f32_e32 v41, 1.0, v41
	v_add_f32_e32 v44, 1.0, v44
	v_add_f32_e32 v45, 1.0, v45
	v_add_f32_e32 v46, 1.0, v46
	v_add_f32_e32 v47, 1.0, v47
	v_rcp_f32_e32 v48, v48
	v_rcp_f32_e32 v31, v31
	v_rcp_f32_e32 v40, v40
	v_rcp_f32_e32 v41, v41
	v_rcp_f32_e32 v44, v44
	v_rcp_f32_e32 v45, v45
	v_rcp_f32_e32 v46, v46
	v_rcp_f32_e32 v47, v47
	v_mul_f32_e32 v23, v23, v48
	v_mul_f32_e32 v31, v43, v31
	v_mul_f32_e32 v25, v25, v40
	v_mul_f32_e32 v33, v33, v41
	v_mul_f32_e32 v27, v27, v44
	v_mul_f32_e32 v35, v35, v45
	v_mul_f32_e32 v21, v21, v46
	v_mul_f32_e32 v29, v29, v47
	v_mul_f32_e32 v23, v22, v23
	v_mul_f32_e32 v31, v42, v31
	v_mul_f32_e32 v24, v24, v25
	v_mul_f32_e32 v25, v32, v33
	v_mul_f32_e32 v26, v26, v27
	v_mul_f32_e32 v27, v34, v35
	v_mul_f32_e32 v32, v20, v21
	v_mul_f32_e32 v28, v28, v29
	v_cvt_pk_bf16_f32 v20, v31, v24
	v_cvt_pk_bf16_f32 v21, v25, v26
	v_cvt_pk_bf16_f32 v22, v27, v32
	v_cvt_pk_bf16_f32 v23, v28, v23
	global_store_dwordx4 v[36:37], v[20:23], off
	v_mov_b32_e32 v28, v16
	v_mov_b32_e32 v29, v8
	v_mov_b32_e32 v8, v17
	s_waitcnt vmcnt(6)
	v_mov_b64_e32 v[20:21], v[180:181]
	v_mov_b64_e32 v[22:23], v[182:183]
	v_mov_b32_e32 v16, v20
	s_waitcnt vmcnt(4)
	v_mov_b64_e32 v[24:25], v[184:185]
	v_mov_b64_e32 v[26:27], v[186:187]
	v_mov_b32_e32 v17, v24
	v_mov_b32_e32 v24, v21
	v_mov_b32_e32 v20, v22
	v_mov_b32_e32 v21, v26
	v_mov_b32_e32 v26, v23
	v_pk_add_f32 v[16:17], v[16:17], v[24:25]
	v_pk_add_f32 v[20:21], v[20:21], v[26:27]
	s_nop 0
	v_pk_add_f32 v[16:17], v[16:17], v[20:21]
	s_nop 0
	v_add_f32_e32 v16, 0, v16
	v_add_f32_e32 v20, v16, v17
	ds_bpermute_b32 v21, v126, v20
	v_mov_b32_e32 v17, v10
	v_mov_b32_e32 v10, v19
	v_mov_b32_e32 v19, v4
	v_mov_b32_e32 v4, v13
	s_waitcnt lgkmcnt(0)
	v_add_f32_e32 v20, v20, v21
	ds_bpermute_b32 v1, v1, v20
	v_mov_b32_e32 v13, v6
	v_mov_b32_e32 v16, v18
	v_mov_b32_e32 v18, v12
	v_mov_b32_e32 v12, v14
	s_waitcnt lgkmcnt(0)
	v_add_f32_e32 v1, v20, v1
	v_fmamk_f32 v1, v1, 0x3a000000, v226
	v_mul_f32_e32 v6, 0x4b800000, v1
	v_cmp_gt_f32_e32 vcc, s71, v1
	s_nop 1
	v_cndmask_b32_e32 v1, v1, v6, vcc
	v_rsq_f32_e32 v1, v1
	v_mov_b32_e32 v6, v15
	v_mad_i64_i32 v[14:15], s[10:11], v30, s72, v[60:61]
	v_mul_f32_e32 v20, 0x45800000, v1
	v_cndmask_b32_e32 v20, v1, v20, vcc
	v_pk_mul_f32 v[6:7], v[6:7], v[20:21] op_sel_hi:[1,0]
	v_pk_mul_f32 v[22:23], v[28:29], v[20:21] op_sel_hi:[1,0]
	v_pk_mul_f32 v[8:9], v[8:9], v[20:21] op_sel_hi:[1,0]
	v_pk_mul_f32 v[16:17], v[16:17], v[20:21] op_sel_hi:[1,0]
	v_pk_mul_f32 v[10:11], v[10:11], v[20:21] op_sel_hi:[1,0]
	v_pk_mul_f32 v[18:19], v[18:19], v[20:21] op_sel_hi:[1,0]
	v_pk_mul_f32 v[4:5], v[4:5], v[20:21] op_sel_hi:[1,0]
	v_pk_mul_f32 v[12:13], v[12:13], v[20:21] op_sel_hi:[1,0]
	v_mul_f32_e32 v28, 0xbfb8aa3b, v7
	v_mul_f32_e32 v1, 0xbfb8aa3b, v23
	v_mul_f32_e32 v20, 0xbfb8aa3b, v9
	v_mul_f32_e32 v21, 0xbfb8aa3b, v17
	v_mul_f32_e32 v24, 0xbfb8aa3b, v11
	v_mul_f32_e32 v25, 0xbfb8aa3b, v19
	v_mul_f32_e32 v26, 0xbfb8aa3b, v5
	v_mul_f32_e32 v27, 0xbfb8aa3b, v13
	v_exp_f32_e32 v28, v28
	v_exp_f32_e32 v1, v1
	v_exp_f32_e32 v20, v20
	v_exp_f32_e32 v21, v21
	v_exp_f32_e32 v24, v24
	v_exp_f32_e32 v25, v25
	v_exp_f32_e32 v26, v26
	v_exp_f32_e32 v27, v27
	v_add_f32_e32 v28, 1.0, v28
	v_add_f32_e32 v1, 1.0, v1
	v_add_f32_e32 v20, 1.0, v20
	v_add_f32_e32 v21, 1.0, v21
	v_add_f32_e32 v24, 1.0, v24
	v_add_f32_e32 v25, 1.0, v25
	v_add_f32_e32 v26, 1.0, v26
	v_add_f32_e32 v27, 1.0, v27
	v_rcp_f32_e32 v28, v28
	v_rcp_f32_e32 v1, v1
	v_rcp_f32_e32 v20, v20
	v_rcp_f32_e32 v21, v21
	v_rcp_f32_e32 v24, v24
	v_rcp_f32_e32 v25, v25
	v_rcp_f32_e32 v26, v26
	v_rcp_f32_e32 v27, v27
	v_mul_f32_e32 v7, v7, v28
	v_mul_f32_e32 v1, v23, v1
	v_mul_f32_e32 v9, v9, v20
	v_mul_f32_e32 v17, v17, v21
	v_mul_f32_e32 v11, v11, v24
	v_mul_f32_e32 v19, v19, v25
	v_mul_f32_e32 v5, v5, v26
	v_mul_f32_e32 v13, v13, v27
	v_mul_f32_e32 v7, v6, v7
	v_lshl_add_u64 v[2:3], v[14:15], 0, v[2:3]
	v_mul_f32_e32 v1, v22, v1
	v_mul_f32_e32 v8, v8, v9
	v_mul_f32_e32 v9, v16, v17
	v_mul_f32_e32 v10, v10, v11
	v_mul_f32_e32 v11, v18, v19
	v_mul_f32_e32 v16, v4, v5
	v_mul_f32_e32 v12, v12, v13
	v_cvt_pk_bf16_f32 v4, v1, v8
	v_cvt_pk_bf16_f32 v5, v9, v10
	v_cvt_pk_bf16_f32 v6, v11, v16
	v_cvt_pk_bf16_f32 v7, v12, v7
	global_store_dwordx4 v[2:3], v[4:7], off
	s_andn2_b64 vcc, exec, s[26:27]
	s_mov_b64 s[10:11], -1
	s_cbranch_vccnz .LBB0_422

.LBB0_1053:
	s_lshl_b32 s100, s34, 8
	s_cmp_eq_u32 s71, 2
	s_cselect_b32 s101, 0x80, 0
	s_or_b32 s100, s100, s101
	v_add_u32_e32 v156, s100, v219
	v_lshlrev_b32_e32 v157, 8, v156
	v_mov_b32_e32 v159, 0
	v_add_u32_e32 v158, 0, v157
	v_lshl_add_u64 v[160:161], v[158:159], 0, v[204:205]
	global_load_dwordx4 v[164:167], v[160:161], off
	global_load_dwordx4 v[168:171], v[160:161], off offset:16
	global_load_dwordx4 v[172:175], v[160:161], off offset:32
	global_load_dwordx4 v[176:179], v[160:161], off offset:48
	v_add_u32_e32 v158, 0x1000, v157
	v_lshl_add_u64 v[160:161], v[158:159], 0, v[204:205]
	global_load_dwordx4 v[180:183], v[160:161], off
	global_load_dwordx4 v[184:187], v[160:161], off offset:16
	global_load_dwordx4 v[188:191], v[160:161], off offset:32
	global_load_dwordx4 v[192:195], v[160:161], off offset:48
	s_and_b64 vcc, exec, s[16:17]
	s_cbranch_vccz .LBB0_1055
	s_barrier
.LBB0_1055:
	s_lshl_b32 s21, s34, 8
	s_cmp_eq_u32 s71, 2
	s_cselect_b32 s23, 0x80, 0
	s_or_b32 s21, s21, s23
	v_add_u32_e32 v132, s21, v219
	v_ashrrev_i32_e32 v133, 31, v132
	v_lshlrev_b64 v[2:3], 8, v[132:133]
	v_lshl_add_u64 v[2:3], v[204:205], 0, v[2:3]
	v_mov_b32_e32 v150, v128
	v_mov_b32_e32 v151, v124
	v_mov_b32_e32 v124, v129
	v_mov_b32_e32 v152, v130
	v_mov_b32_e32 v153, v126
	v_mov_b32_e32 v126, v131
	v_and_b32_e32 v3, 64, v225
	v_xor_b32_e32 v1, 16, v225
	v_add_u32_e32 v3, 64, v3
	v_cmp_lt_i32_e32 vcc, v1, v3
	v_xor_b32_e32 v133, 32, v225
	v_lshl_or_b32 v2, s72, 7, v221
	v_cndmask_b32_e32 v1, v225, v1, vcc
	v_lshlrev_b32_e32 v1, 2, v1
	v_cmp_lt_i32_e32 vcc, v133, v3
	s_waitcnt vmcnt(4)
	v_mov_b64_e32 v[134:135], v[164:165]
	v_mov_b64_e32 v[136:137], v[166:167]
	v_mov_b64_e32 v[138:139], v[168:169]
	v_mov_b64_e32 v[140:141], v[170:171]
	v_mov_b64_e32 v[142:143], v[172:173]
	v_mov_b64_e32 v[144:145], v[174:175]
	v_mov_b64_e32 v[146:147], v[176:177]
	v_mov_b64_e32 v[148:149], v[178:179]
	v_add_u32_e32 v158, 0x2000, v157
	v_lshl_add_u64 v[160:161], v[158:159], 0, v[204:205]
	global_load_dwordx4 v[164:167], v[160:161], off
	global_load_dwordx4 v[168:171], v[160:161], off offset:16
	global_load_dwordx4 v[172:175], v[160:161], off offset:32
	global_load_dwordx4 v[176:179], v[160:161], off offset:48
	v_mov_b32_e32 v128, v135
	v_mov_b32_e32 v129, v136
	v_mov_b32_e32 v135, v137
	v_mov_b32_e32 v130, v139
	v_mov_b32_e32 v131, v140
	v_mov_b32_e32 v139, v141
	v_add_f32_e32 v136, v142, v143
	v_add_f32_e32 v140, v144, v145
	v_mov_b32_e32 v137, v148
	v_mov_b32_e32 v141, v149
	v_pk_add_f32 v[128:129], v[128:129], v[134:135]
	v_pk_add_f32 v[130:131], v[130:131], v[138:139]
	v_pk_add_f32 v[134:135], v[136:137], v[140:141]
	v_add_f32_e32 v136, v128, v129
	v_pk_add_f32 v[128:129], v[130:131], v[130:131] op_sel:[0,1] op_sel_hi:[1,0]
	v_mov_b32_e32 v143, v146
	v_add_f32_e32 v142, 0, v136
	v_mov_b32_e32 v129, v147
	v_pk_add_f32 v[128:129], v[142:143], v[128:129]
	v_cndmask_b32_e32 v3, v225, v133, vcc
	v_pk_add_f32 v[128:129], v[128:129], v[134:135]
	v_mov_b32_e32 v130, v116
	v_add_f32_e32 v129, v128, v129
	ds_bpermute_b32 v131, v1, v129
	v_lshlrev_b32_e32 v128, 2, v3
	v_mov_b32_e32 v134, v118
	v_mov_b32_e32 v135, v122
	v_mov_b32_e32 v122, v119
	s_waitcnt lgkmcnt(0)
	v_add_f32_e32 v3, v129, v131
	ds_bpermute_b32 v116, v128, v3
	v_mov_b32_e32 v131, v120
	v_mov_b32_e32 v120, v117
	s_waitcnt lgkmcnt(0)
	v_add_f32_e32 v3, v3, v116
	v_fmamk_f32 v3, v3, 0x3a000000, v226
	v_mul_f32_e32 v116, 0x4b800000, v3
	v_cmp_gt_f32_e32 vcc, s67, v3
	s_nop 1
	v_cndmask_b32_e32 v3, v3, v116, vcc
	v_rsq_f32_e32 v118, v3
	v_mov_b64_e32 v[116:117], s[12:13]
	v_ashrrev_i32_e32 v3, 31, v2
	v_lshlrev_b64 v[2:3], 1, v[2:3]
	v_mul_f32_e32 v119, 0x45800000, v118
	v_cndmask_b32_e32 v118, v118, v119, vcc
	v_pk_mul_f32 v[136:137], v[150:151], v[118:119] op_sel_hi:[1,0]
	v_pk_mul_f32 v[124:125], v[124:125], v[118:119] op_sel_hi:[1,0]
	v_pk_mul_f32 v[138:139], v[152:153], v[118:119] op_sel_hi:[1,0]
	v_pk_mul_f32 v[126:127], v[126:127], v[118:119] op_sel_hi:[1,0]
	v_pk_mul_f32 v[130:131], v[130:131], v[118:119] op_sel_hi:[1,0]
	v_pk_mul_f32 v[120:121], v[120:121], v[118:119] op_sel_hi:[1,0]
	v_pk_mul_f32 v[134:135], v[134:135], v[118:119] op_sel_hi:[1,0]
	v_pk_mul_f32 v[118:119], v[122:123], v[118:119] op_sel_hi:[1,0]
	v_mul_f32_e32 v122, 0xbfb8aa3b, v137
	v_mul_f32_e32 v123, 0xbfb8aa3b, v125
	v_mul_f32_e32 v129, 0xbfb8aa3b, v139
	v_mul_f32_e32 v133, 0xbfb8aa3b, v127
	v_mul_f32_e32 v140, 0xbfb8aa3b, v131
	v_mul_f32_e32 v141, 0xbfb8aa3b, v121
	v_mul_f32_e32 v142, 0xbfb8aa3b, v135
	v_mul_f32_e32 v143, 0xbfb8aa3b, v119
	v_exp_f32_e32 v122, v122
	v_exp_f32_e32 v123, v123
	v_exp_f32_e32 v129, v129
	v_exp_f32_e32 v133, v133
	v_exp_f32_e32 v140, v140
	v_exp_f32_e32 v141, v141
	v_exp_f32_e32 v142, v142
	v_exp_f32_e32 v143, v143
	v_add_f32_e32 v122, 1.0, v122
	v_add_f32_e32 v123, 1.0, v123
	v_add_f32_e32 v129, 1.0, v129
	v_add_f32_e32 v133, 1.0, v133
	v_add_f32_e32 v140, 1.0, v140
	v_add_f32_e32 v141, 1.0, v141
	v_add_f32_e32 v142, 1.0, v142
	v_add_f32_e32 v143, 1.0, v143
	v_rcp_f32_e32 v122, v122
	v_rcp_f32_e32 v123, v123
	v_rcp_f32_e32 v129, v129
	v_rcp_f32_e32 v133, v133
	v_rcp_f32_e32 v140, v140
	v_rcp_f32_e32 v141, v141
	v_rcp_f32_e32 v142, v142
	v_rcp_f32_e32 v143, v143
	v_mul_f32_e32 v122, v137, v122
	v_mul_f32_e32 v123, v125, v123
	v_mul_f32_e32 v125, v139, v129
	v_mul_f32_e32 v127, v127, v133
	v_mul_f32_e32 v129, v131, v140
	v_mul_f32_e32 v121, v121, v141
	v_mul_f32_e32 v131, v135, v142
	v_mul_f32_e32 v119, v119, v143
	v_mul_f32_e32 v122, v136, v122
	v_mul_f32_e32 v123, v124, v123
	v_mul_f32_e32 v124, v138, v125
	v_mul_f32_e32 v125, v126, v127
	v_mul_f32_e32 v126, v130, v129
	v_mul_f32_e32 v120, v120, v121
	v_mul_f32_e32 v121, v134, v131
	v_mul_f32_e32 v127, v118, v119
	v_cvt_pk_bf16_f32 v118, v122, v123
	v_cvt_pk_bf16_f32 v119, v124, v125
	v_cvt_pk_bf16_f32 v120, v126, v120
	v_mad_i64_i32 v[122:123], s[36:37], v132, s68, v[116:117]
	v_or_b32_e32 v126, 16, v132
	v_cvt_pk_bf16_f32 v121, v121, v127
	v_lshl_add_u64 v[122:123], v[122:123], 0, v[2:3]
	v_ashrrev_i32_e32 v127, 31, v126
	global_store_dwordx4 v[122:123], v[118:121], off
	s_nop 1
	v_lshlrev_b64 v[118:119], 8, v[126:127]
	v_lshl_add_u64 v[130:131], v[204:205], 0, v[118:119]
	v_mov_b32_e32 v131, v104
	v_mov_b32_e32 v104, v113
	v_mov_b32_e32 v113, v106
	v_mov_b32_e32 v106, v115
	v_mov_b32_e32 v115, v100
	v_mov_b32_e32 v130, v112
	v_mov_b32_e32 v112, v114
	v_mov_b32_e32 v114, v108
	v_mov_b32_e32 v108, v110
	s_waitcnt vmcnt(8)
	v_mov_b64_e32 v[118:119], v[180:181]
	v_mov_b64_e32 v[120:121], v[182:183]
	v_add_u32_e32 v158, 0x3000, v157
	v_lshl_add_u64 v[160:161], v[158:159], 0, v[204:205]
	global_load_dwordx4 v[180:183], v[160:161], off
	v_mov_b32_e32 v142, v119
	v_mov_b32_e32 v143, v120
	v_mov_b32_e32 v119, v121
	s_waitcnt vmcnt(8)
	v_mov_b64_e32 v[122:123], v[184:185]
	v_mov_b64_e32 v[124:125], v[186:187]
	global_load_dwordx4 v[184:187], v[160:161], off offset:16
	v_mov_b32_e32 v120, v123
	v_mov_b32_e32 v121, v124
	v_mov_b32_e32 v123, v125
	v_pk_add_f32 v[118:119], v[142:143], v[118:119]
	v_pk_add_f32 v[120:121], v[120:121], v[122:123]
	v_add_f32_e32 v100, v118, v119
	v_pk_add_f32 v[118:119], v[120:121], v[120:121] op_sel:[0,1] op_sel_hi:[1,0]
	s_waitcnt vmcnt(8)
	v_mov_b64_e32 v[134:135], v[188:189]
	v_mov_b64_e32 v[136:137], v[190:191]
	global_load_dwordx4 v[188:191], v[160:161], off offset:32
	v_add_f32_e32 v124, v134, v135
	v_add_f32_e32 v134, v136, v137
	s_waitcnt vmcnt(8)
	v_mov_b64_e32 v[138:139], v[192:193]
	v_mov_b64_e32 v[140:141], v[194:195]
	global_load_dwordx4 v[192:195], v[160:161], off offset:48
	v_mov_b32_e32 v137, v138
	v_mov_b32_e32 v125, v140
	v_mov_b32_e32 v135, v141
	v_add_f32_e32 v136, 0, v100
	v_mov_b32_e32 v119, v139
	v_pk_add_f32 v[122:123], v[124:125], v[134:135]
	v_pk_add_f32 v[118:119], v[136:137], v[118:119]
	v_mov_b32_e32 v100, v109
	v_pk_add_f32 v[118:119], v[118:119], v[122:123]
	v_mov_b32_e32 v109, v102
	v_add_f32_e32 v118, v118, v119
	ds_bpermute_b32 v119, v1, v118
	v_mov_b32_e32 v102, v111
	v_mad_i64_i32 v[110:111], s[36:37], v126, s68, v[116:117]
	v_lshl_add_u64 v[110:111], v[110:111], 0, v[2:3]
	s_waitcnt lgkmcnt(0)
	v_add_f32_e32 v120, v118, v119
	ds_bpermute_b32 v121, v128, v120
	v_or_b32_e32 v118, 32, v132
	v_ashrrev_i32_e32 v119, 31, v118
	s_waitcnt lgkmcnt(0)
	v_add_f32_e32 v120, v120, v121
	v_fmamk_f32 v120, v120, 0x3a000000, v226
	v_mul_f32_e32 v121, 0x4b800000, v120
	v_cmp_gt_f32_e32 vcc, s67, v120
	s_nop 1
	v_cndmask_b32_e32 v120, v120, v121, vcc
	v_rsq_f32_e32 v122, v120
	v_lshlrev_b64 v[120:121], 8, v[118:119]
	v_lshl_add_u64 v[120:121], v[204:205], 0, v[120:121]
	v_mul_f32_e32 v119, 0x45800000, v122
	v_cndmask_b32_e32 v122, v122, v119, vcc
	v_pk_mul_f32 v[102:103], v[102:103], v[122:123] op_sel_hi:[1,0]
	v_pk_mul_f32 v[124:125], v[130:131], v[122:123] op_sel_hi:[1,0]
	v_pk_mul_f32 v[104:105], v[104:105], v[122:123] op_sel_hi:[1,0]
	v_pk_mul_f32 v[112:113], v[112:113], v[122:123] op_sel_hi:[1,0]
	v_pk_mul_f32 v[106:107], v[106:107], v[122:123] op_sel_hi:[1,0]
	v_pk_mul_f32 v[114:115], v[114:115], v[122:123] op_sel_hi:[1,0]
	v_pk_mul_f32 v[100:101], v[100:101], v[122:123] op_sel_hi:[1,0]
	v_pk_mul_f32 v[108:109], v[108:109], v[122:123] op_sel_hi:[1,0]
	v_mul_f32_e32 v131, 0xbfb8aa3b, v103
	v_mul_f32_e32 v119, 0xbfb8aa3b, v125
	v_mul_f32_e32 v122, 0xbfb8aa3b, v105
	v_mul_f32_e32 v123, 0xbfb8aa3b, v113
	v_mul_f32_e32 v126, 0xbfb8aa3b, v107
	v_mul_f32_e32 v127, 0xbfb8aa3b, v115
	v_mul_f32_e32 v129, 0xbfb8aa3b, v101
	v_mul_f32_e32 v130, 0xbfb8aa3b, v109
	v_exp_f32_e32 v131, v131
	v_exp_f32_e32 v119, v119
	v_exp_f32_e32 v122, v122
	v_exp_f32_e32 v123, v123
	v_exp_f32_e32 v126, v126
	v_exp_f32_e32 v127, v127
	v_exp_f32_e32 v129, v129
	v_exp_f32_e32 v130, v130
	v_add_f32_e32 v131, 1.0, v131
	v_add_f32_e32 v119, 1.0, v119
	v_add_f32_e32 v122, 1.0, v122
	v_add_f32_e32 v123, 1.0, v123
	v_add_f32_e32 v126, 1.0, v126
	v_add_f32_e32 v127, 1.0, v127
	v_add_f32_e32 v129, 1.0, v129
	v_add_f32_e32 v130, 1.0, v130
	v_rcp_f32_e32 v131, v131
	v_rcp_f32_e32 v119, v119
	v_rcp_f32_e32 v122, v122
	v_rcp_f32_e32 v123, v123
	v_rcp_f32_e32 v126, v126
	v_rcp_f32_e32 v127, v127
	v_rcp_f32_e32 v129, v129
	v_rcp_f32_e32 v130, v130
	v_mul_f32_e32 v103, v103, v131
	v_mul_f32_e32 v119, v125, v119
	v_mul_f32_e32 v105, v105, v122
	v_mul_f32_e32 v113, v113, v123
	v_mul_f32_e32 v107, v107, v126
	v_mul_f32_e32 v115, v115, v127
	v_mul_f32_e32 v101, v101, v129
	v_mul_f32_e32 v109, v109, v130
	v_mul_f32_e32 v103, v102, v103
	v_mul_f32_e32 v119, v124, v119
	v_mul_f32_e32 v104, v104, v105
	v_mul_f32_e32 v105, v112, v113
	v_mul_f32_e32 v106, v106, v107
	v_mul_f32_e32 v107, v114, v115
	v_mul_f32_e32 v112, v100, v101
	v_mul_f32_e32 v108, v108, v109
	v_cvt_pk_bf16_f32 v100, v119, v104
	v_cvt_pk_bf16_f32 v101, v105, v106
	v_cvt_pk_bf16_f32 v102, v107, v112
	v_cvt_pk_bf16_f32 v103, v108, v103
	global_store_dwordx4 v[110:111], v[100:103], off
	v_mov_b32_e32 v121, v88
	v_mov_b32_e32 v88, v97
	v_mov_b32_e32 v97, v90
	v_mov_b32_e32 v90, v99
	v_mov_b32_e32 v99, v84
	v_mov_b32_e32 v120, v96
	v_mov_b32_e32 v96, v98
	v_mov_b32_e32 v98, v92
	v_mov_b32_e32 v92, v94
	s_waitcnt vmcnt(9)
	v_mov_b64_e32 v[100:101], v[164:165]
	v_mov_b64_e32 v[102:103], v[166:167]
	v_add_u32_e32 v158, 0x8000, v157
	v_lshl_add_u64 v[160:161], v[158:159], 0, v[204:205]
	global_load_dwordx4 v[164:167], v[160:161], off
	v_mov_b32_e32 v122, v101
	v_mov_b32_e32 v123, v102
	v_mov_b32_e32 v101, v103
	s_waitcnt vmcnt(9)
	v_mov_b64_e32 v[104:105], v[168:169]
	v_mov_b64_e32 v[106:107], v[170:171]
	global_load_dwordx4 v[168:171], v[160:161], off offset:16
	v_mov_b32_e32 v102, v105
	v_mov_b32_e32 v103, v106
	v_mov_b32_e32 v105, v107
	v_pk_add_f32 v[100:101], v[122:123], v[100:101]
	v_pk_add_f32 v[102:103], v[102:103], v[104:105]
	v_add_f32_e32 v84, v100, v101
	v_pk_add_f32 v[100:101], v[102:103], v[102:103] op_sel:[0,1] op_sel_hi:[1,0]
	s_waitcnt vmcnt(9)
	v_mov_b64_e32 v[108:109], v[172:173]
	v_mov_b64_e32 v[110:111], v[174:175]
	global_load_dwordx4 v[172:175], v[160:161], off offset:32
	v_add_f32_e32 v106, v108, v109
	v_add_f32_e32 v108, v110, v111
	s_waitcnt vmcnt(9)
	v_mov_b64_e32 v[112:113], v[176:177]
	v_mov_b64_e32 v[114:115], v[178:179]
	global_load_dwordx4 v[176:179], v[160:161], off offset:48
	v_mov_b32_e32 v111, v112
	v_mov_b32_e32 v107, v114
	v_mov_b32_e32 v109, v115
	v_add_f32_e32 v110, 0, v84
	v_mov_b32_e32 v101, v113
	v_pk_add_f32 v[104:105], v[106:107], v[108:109]
	v_pk_add_f32 v[100:101], v[110:111], v[100:101]
	v_mov_b32_e32 v84, v93
	v_pk_add_f32 v[100:101], v[100:101], v[104:105]
	v_mov_b32_e32 v93, v86
	v_add_f32_e32 v100, v100, v101
	ds_bpermute_b32 v101, v1, v100
	v_mov_b32_e32 v86, v95
	v_mad_i64_i32 v[94:95], s[36:37], v118, s68, v[116:117]
	v_lshl_add_u64 v[94:95], v[94:95], 0, v[2:3]
	s_waitcnt lgkmcnt(0)
	v_add_f32_e32 v102, v100, v101
	ds_bpermute_b32 v103, v128, v102
	v_or_b32_e32 v100, 48, v132
	v_ashrrev_i32_e32 v101, 31, v100
	s_waitcnt lgkmcnt(0)
	v_add_f32_e32 v102, v102, v103
	v_fmamk_f32 v102, v102, 0x3a000000, v226
	v_mul_f32_e32 v103, 0x4b800000, v102
	v_cmp_gt_f32_e32 vcc, s67, v102
	s_nop 1
	v_cndmask_b32_e32 v102, v102, v103, vcc
	v_rsq_f32_e32 v104, v102
	v_lshlrev_b64 v[102:103], 8, v[100:101]
	v_lshl_add_u64 v[102:103], v[204:205], 0, v[102:103]
	v_mul_f32_e32 v101, 0x45800000, v104
	v_cndmask_b32_e32 v104, v104, v101, vcc
	v_pk_mul_f32 v[86:87], v[86:87], v[104:105] op_sel_hi:[1,0]
	v_pk_mul_f32 v[106:107], v[120:121], v[104:105] op_sel_hi:[1,0]
	v_pk_mul_f32 v[88:89], v[88:89], v[104:105] op_sel_hi:[1,0]
	v_pk_mul_f32 v[96:97], v[96:97], v[104:105] op_sel_hi:[1,0]
	v_pk_mul_f32 v[90:91], v[90:91], v[104:105] op_sel_hi:[1,0]
	v_pk_mul_f32 v[98:99], v[98:99], v[104:105] op_sel_hi:[1,0]
	v_pk_mul_f32 v[84:85], v[84:85], v[104:105] op_sel_hi:[1,0]
	v_pk_mul_f32 v[92:93], v[92:93], v[104:105] op_sel_hi:[1,0]
	v_mul_f32_e32 v112, 0xbfb8aa3b, v87
	v_mul_f32_e32 v101, 0xbfb8aa3b, v107
	v_mul_f32_e32 v104, 0xbfb8aa3b, v89
	v_mul_f32_e32 v105, 0xbfb8aa3b, v97
	v_mul_f32_e32 v108, 0xbfb8aa3b, v91
	v_mul_f32_e32 v109, 0xbfb8aa3b, v99
	v_mul_f32_e32 v110, 0xbfb8aa3b, v85
	v_mul_f32_e32 v111, 0xbfb8aa3b, v93
	v_exp_f32_e32 v112, v112
	v_exp_f32_e32 v101, v101
	v_exp_f32_e32 v104, v104
	v_exp_f32_e32 v105, v105
	v_exp_f32_e32 v108, v108
	v_exp_f32_e32 v109, v109
	v_exp_f32_e32 v110, v110
	v_exp_f32_e32 v111, v111
	v_add_f32_e32 v112, 1.0, v112
	v_add_f32_e32 v101, 1.0, v101
	v_add_f32_e32 v104, 1.0, v104
	v_add_f32_e32 v105, 1.0, v105
	v_add_f32_e32 v108, 1.0, v108
	v_add_f32_e32 v109, 1.0, v109
	v_add_f32_e32 v110, 1.0, v110
	v_add_f32_e32 v111, 1.0, v111
	v_rcp_f32_e32 v112, v112
	v_rcp_f32_e32 v101, v101
	v_rcp_f32_e32 v104, v104
	v_rcp_f32_e32 v105, v105
	v_rcp_f32_e32 v108, v108
	v_rcp_f32_e32 v109, v109
	v_rcp_f32_e32 v110, v110
	v_rcp_f32_e32 v111, v111
	v_mul_f32_e32 v87, v87, v112
	v_mul_f32_e32 v101, v107, v101
	v_mul_f32_e32 v89, v89, v104
	v_mul_f32_e32 v97, v97, v105
	v_mul_f32_e32 v91, v91, v108
	v_mul_f32_e32 v99, v99, v109
	v_mul_f32_e32 v85, v85, v110
	v_mul_f32_e32 v93, v93, v111
	v_mul_f32_e32 v87, v86, v87
	v_mul_f32_e32 v101, v106, v101
	v_mul_f32_e32 v88, v88, v89
	v_mul_f32_e32 v89, v96, v97
	v_mul_f32_e32 v90, v90, v91
	v_mul_f32_e32 v91, v98, v99
	v_mul_f32_e32 v96, v84, v85
	v_mul_f32_e32 v92, v92, v93
	v_cvt_pk_bf16_f32 v84, v101, v88
	v_cvt_pk_bf16_f32 v85, v89, v90
	v_cvt_pk_bf16_f32 v86, v91, v96
	v_cvt_pk_bf16_f32 v87, v92, v87
	global_store_dwordx4 v[94:95], v[84:87], off
	v_mov_b32_e32 v103, v76
	v_mov_b32_e32 v76, v81
	v_mov_b32_e32 v102, v80
	v_mov_b32_e32 v80, v82
	v_mov_b32_e32 v82, v68
	v_mov_b32_e32 v68, v70
	s_waitcnt vmcnt(9)
	v_mov_b64_e32 v[84:85], v[180:181]
	v_mov_b64_e32 v[86:87], v[182:183]
	v_add_u32_e32 v158, 0x9000, v157
	v_lshl_add_u64 v[160:161], v[158:159], 0, v[204:205]
	global_load_dwordx4 v[180:183], v[160:161], off
	v_mov_b32_e32 v104, v85
	v_mov_b32_e32 v105, v86
	v_mov_b32_e32 v85, v87
	s_waitcnt vmcnt(9)
	v_mov_b64_e32 v[88:89], v[184:185]
	v_mov_b64_e32 v[90:91], v[186:187]
	global_load_dwordx4 v[184:187], v[160:161], off offset:16
	v_mov_b32_e32 v86, v89
	v_mov_b32_e32 v87, v90
	v_mov_b32_e32 v89, v91
	v_pk_add_f32 v[84:85], v[104:105], v[84:85]
	v_pk_add_f32 v[86:87], v[86:87], v[88:89]
	v_add_f32_e32 v81, v84, v85
	v_pk_add_f32 v[84:85], v[86:87], v[86:87] op_sel:[0,1] op_sel_hi:[1,0]
	s_waitcnt vmcnt(9)
	v_mov_b64_e32 v[92:93], v[188:189]
	v_mov_b64_e32 v[94:95], v[190:191]
	global_load_dwordx4 v[188:191], v[160:161], off offset:32
	v_add_f32_e32 v90, v92, v93
	v_add_f32_e32 v92, v94, v95
	s_waitcnt vmcnt(9)
	v_mov_b64_e32 v[96:97], v[192:193]
	v_mov_b64_e32 v[98:99], v[194:195]
	global_load_dwordx4 v[192:195], v[160:161], off offset:48
	v_mov_b32_e32 v95, v96
	v_mov_b32_e32 v91, v98
	v_mov_b32_e32 v93, v99
	v_add_f32_e32 v94, 0, v81
	v_mov_b32_e32 v85, v97
	v_pk_add_f32 v[88:89], v[90:91], v[92:93]
	v_pk_add_f32 v[84:85], v[94:95], v[84:85]
	v_mov_b32_e32 v81, v78
	v_pk_add_f32 v[84:85], v[84:85], v[88:89]
	v_mov_b32_e32 v78, v83
	v_add_f32_e32 v84, v84, v85
	ds_bpermute_b32 v85, v1, v84
	v_mov_b32_e32 v83, v72
	v_mov_b32_e32 v72, v69
	v_mov_b32_e32 v69, v74
	v_mov_b32_e32 v74, v71
	s_waitcnt lgkmcnt(0)
	v_add_f32_e32 v84, v84, v85
	ds_bpermute_b32 v85, v128, v84
	s_waitcnt lgkmcnt(0)
	v_add_f32_e32 v70, v84, v85
	v_fmamk_f32 v70, v70, 0x3a000000, v226
	v_mul_f32_e32 v71, 0x4b800000, v70
	v_cmp_gt_f32_e32 vcc, s67, v70
	s_nop 1
	v_cndmask_b32_e32 v70, v70, v71, vcc
	v_rsq_f32_e32 v86, v70
	v_mad_i64_i32 v[70:71], s[36:37], v100, s68, v[116:117]
	v_lshl_add_u64 v[84:85], v[70:71], 0, v[2:3]
	v_mul_f32_e32 v70, 0x45800000, v86
	v_cndmask_b32_e32 v70, v86, v70, vcc
	v_pk_mul_f32 v[86:87], v[102:103], v[70:71] op_sel_hi:[1,0]
	v_pk_mul_f32 v[76:77], v[76:77], v[70:71] op_sel_hi:[1,0]
	v_pk_mul_f32 v[80:81], v[80:81], v[70:71] op_sel_hi:[1,0]
	v_pk_mul_f32 v[78:79], v[78:79], v[70:71] op_sel_hi:[1,0]
	v_pk_mul_f32 v[82:83], v[82:83], v[70:71] op_sel_hi:[1,0]
	v_pk_mul_f32 v[72:73], v[72:73], v[70:71] op_sel_hi:[1,0]
	v_pk_mul_f32 v[68:69], v[68:69], v[70:71] op_sel_hi:[1,0]
	v_pk_mul_f32 v[70:71], v[74:75], v[70:71] op_sel_hi:[1,0]
	v_mul_f32_e32 v74, 0xbfb8aa3b, v87
	v_mul_f32_e32 v93, 0xbfb8aa3b, v71
	v_mul_f32_e32 v75, 0xbfb8aa3b, v77
	v_mul_f32_e32 v88, 0xbfb8aa3b, v81
	v_mul_f32_e32 v89, 0xbfb8aa3b, v79
	v_mul_f32_e32 v90, 0xbfb8aa3b, v83
	v_mul_f32_e32 v91, 0xbfb8aa3b, v73
	v_mul_f32_e32 v92, 0xbfb8aa3b, v69
	v_exp_f32_e32 v93, v93
	v_exp_f32_e32 v74, v74
	v_exp_f32_e32 v75, v75
	v_exp_f32_e32 v88, v88
	v_exp_f32_e32 v89, v89
	v_exp_f32_e32 v90, v90
	v_exp_f32_e32 v91, v91
	v_exp_f32_e32 v92, v92
	v_add_f32_e32 v93, 1.0, v93
	v_add_f32_e32 v74, 1.0, v74
	v_add_f32_e32 v75, 1.0, v75
	v_add_f32_e32 v88, 1.0, v88
	v_add_f32_e32 v89, 1.0, v89
	v_add_f32_e32 v90, 1.0, v90
	v_add_f32_e32 v91, 1.0, v91
	v_add_f32_e32 v92, 1.0, v92
	v_rcp_f32_e32 v93, v93
	v_rcp_f32_e32 v74, v74
	v_rcp_f32_e32 v75, v75
	v_rcp_f32_e32 v88, v88
	v_rcp_f32_e32 v89, v89
	v_rcp_f32_e32 v90, v90
	v_rcp_f32_e32 v91, v91
	v_rcp_f32_e32 v92, v92
	v_mul_f32_e32 v71, v71, v93
	v_mul_f32_e32 v74, v87, v74
	v_mul_f32_e32 v75, v77, v75
	v_mul_f32_e32 v77, v81, v88
	v_mul_f32_e32 v79, v79, v89
	v_mul_f32_e32 v81, v83, v90
	v_mul_f32_e32 v73, v73, v91
	v_mul_f32_e32 v69, v69, v92
	v_mul_f32_e32 v71, v70, v71
	v_mul_f32_e32 v74, v86, v74
	v_mul_f32_e32 v75, v76, v75
	v_mul_f32_e32 v76, v80, v77
	v_mul_f32_e32 v77, v78, v79
	v_mul_f32_e32 v78, v82, v81
	v_mul_f32_e32 v72, v72, v73
	v_mul_f32_e32 v73, v68, v69
	v_cvt_pk_bf16_f32 v68, v74, v75
	v_cvt_pk_bf16_f32 v69, v76, v77
	v_cvt_pk_bf16_f32 v70, v78, v72
	v_cvt_pk_bf16_f32 v71, v73, v71
	global_store_dwordx4 v[84:85], v[68:71], off
	s_and_b64 vcc, exec, s[8:9]
	s_cbranch_vccz .LBB0_1057
	s_waitcnt vmcnt(0)
	s_andn2_b64 vcc, exec, s[24:25]
	s_mov_b64 s[8:9], -1
	s_cbranch_vccnz .LBB0_1036
	s_branch .LBB0_1058
.LBB0_1057:
	v_add_u32_e32 v84, 0x80, v132
	v_ashrrev_i32_e32 v85, 31, v84
	v_lshlrev_b64 v[68:69], 8, v[84:85]
	v_lshl_add_u64 v[80:81], v[204:205], 0, v[68:69]
	s_nop 0
	v_mov_b32_e32 v86, v64
	v_mov_b32_e32 v87, v56
	v_mov_b32_e32 v56, v65
	v_mov_b32_e32 v64, v66
	v_mov_b32_e32 v65, v58
	v_mov_b32_e32 v58, v67
	v_mov_b32_e32 v66, v60
	v_mov_b32_e32 v67, v52
	v_mov_b32_e32 v52, v61
	s_waitcnt vmcnt(9)
	v_mov_b64_e32 v[68:69], v[164:165]
	v_mov_b64_e32 v[70:71], v[166:167]
	v_add_u32_e32 v158, 0xa000, v157
	v_lshl_add_u64 v[160:161], v[158:159], 0, v[204:205]
	global_load_dwordx4 v[164:167], v[160:161], off
	v_mov_b32_e32 v60, v69
	v_mov_b32_e32 v61, v70
	v_mov_b32_e32 v69, v71
	s_waitcnt vmcnt(9)
	v_mov_b64_e32 v[72:73], v[168:169]
	v_mov_b64_e32 v[74:75], v[170:171]
	global_load_dwordx4 v[168:171], v[160:161], off offset:16
	v_mov_b32_e32 v70, v73
	v_mov_b32_e32 v71, v74
	v_mov_b32_e32 v73, v75
	v_pk_add_f32 v[60:61], v[60:61], v[68:69]
	v_pk_add_f32 v[68:69], v[70:71], v[72:73]
	v_add_f32_e32 v72, v60, v61
	v_pk_add_f32 v[60:61], v[68:69], v[68:69] op_sel:[0,1] op_sel_hi:[1,0]
	s_waitcnt vmcnt(9)
	v_mov_b64_e32 v[76:77], v[172:173]
	v_mov_b64_e32 v[78:79], v[174:175]
	global_load_dwordx4 v[172:175], v[160:161], off offset:32
	v_add_f32_e32 v74, v76, v77
	v_add_f32_e32 v76, v78, v79
	s_waitcnt vmcnt(9)
	v_mov_b64_e32 v[80:81], v[176:177]
	v_mov_b64_e32 v[82:83], v[178:179]
	global_load_dwordx4 v[176:179], v[160:161], off offset:48
	v_mov_b32_e32 v79, v80
	v_mov_b32_e32 v75, v82
	v_mov_b32_e32 v77, v83
	v_add_f32_e32 v78, 0, v72
	v_mov_b32_e32 v61, v81
	v_pk_add_f32 v[70:71], v[74:75], v[76:77]
	v_pk_add_f32 v[60:61], v[78:79], v[60:61]
	v_mov_b32_e32 v69, v54
	v_pk_add_f32 v[60:61], v[60:61], v[70:71]
	v_mov_b32_e32 v54, v63
	v_add_f32_e32 v70, v60, v61
	ds_bpermute_b32 v71, v1, v70
	v_mov_b32_e32 v68, v62
	v_mov_b64_e32 v[60:61], s[12:13]
	v_mad_i64_i32 v[62:63], s[8:9], v84, s68, v[60:61]
	s_waitcnt lgkmcnt(0)
	v_add_f32_e32 v72, v70, v71
	ds_bpermute_b32 v73, v128, v72
	v_add_u32_e32 v70, 0x90, v132
	v_ashrrev_i32_e32 v71, 31, v70
	v_lshl_add_u64 v[62:63], v[62:63], 0, v[2:3]
	s_waitcnt lgkmcnt(0)
	v_add_f32_e32 v72, v72, v73
	v_fmamk_f32 v72, v72, 0x3a000000, v226
	v_mul_f32_e32 v73, 0x4b800000, v72
	v_cmp_gt_f32_e32 vcc, s67, v72
	s_nop 1
	v_cndmask_b32_e32 v72, v72, v73, vcc
	v_rsq_f32_e32 v74, v72
	v_lshlrev_b64 v[72:73], 8, v[70:71]
	v_lshl_add_u64 v[72:73], v[204:205], 0, v[72:73]
	v_mul_f32_e32 v71, 0x45800000, v74
	v_cndmask_b32_e32 v74, v74, v71, vcc
	v_pk_mul_f32 v[54:55], v[54:55], v[74:75] op_sel_hi:[1,0]
	v_pk_mul_f32 v[76:77], v[86:87], v[74:75] op_sel_hi:[1,0]
	v_pk_mul_f32 v[56:57], v[56:57], v[74:75] op_sel_hi:[1,0]
	v_pk_mul_f32 v[64:65], v[64:65], v[74:75] op_sel_hi:[1,0]
	v_pk_mul_f32 v[58:59], v[58:59], v[74:75] op_sel_hi:[1,0]
	v_pk_mul_f32 v[66:67], v[66:67], v[74:75] op_sel_hi:[1,0]
	v_pk_mul_f32 v[52:53], v[52:53], v[74:75] op_sel_hi:[1,0]
	v_pk_mul_f32 v[68:69], v[68:69], v[74:75] op_sel_hi:[1,0]
	v_mul_f32_e32 v82, 0xbfb8aa3b, v55
	v_mul_f32_e32 v71, 0xbfb8aa3b, v77
	v_mul_f32_e32 v74, 0xbfb8aa3b, v57
	v_mul_f32_e32 v75, 0xbfb8aa3b, v65
	v_mul_f32_e32 v78, 0xbfb8aa3b, v59
	v_mul_f32_e32 v79, 0xbfb8aa3b, v67
	v_mul_f32_e32 v80, 0xbfb8aa3b, v53
	v_mul_f32_e32 v81, 0xbfb8aa3b, v69
	v_exp_f32_e32 v82, v82
	v_exp_f32_e32 v71, v71
	v_exp_f32_e32 v74, v74
	v_exp_f32_e32 v75, v75
	v_exp_f32_e32 v78, v78
	v_exp_f32_e32 v79, v79
	v_exp_f32_e32 v80, v80
	v_exp_f32_e32 v81, v81
	v_add_f32_e32 v82, 1.0, v82
	v_add_f32_e32 v71, 1.0, v71
	v_add_f32_e32 v74, 1.0, v74
	v_add_f32_e32 v75, 1.0, v75
	v_add_f32_e32 v78, 1.0, v78
	v_add_f32_e32 v79, 1.0, v79
	v_add_f32_e32 v80, 1.0, v80
	v_add_f32_e32 v81, 1.0, v81
	v_rcp_f32_e32 v82, v82
	v_rcp_f32_e32 v71, v71
	v_rcp_f32_e32 v74, v74
	v_rcp_f32_e32 v75, v75
	v_rcp_f32_e32 v78, v78
	v_rcp_f32_e32 v79, v79
	v_rcp_f32_e32 v80, v80
	v_rcp_f32_e32 v81, v81
	v_mul_f32_e32 v55, v55, v82
	v_mul_f32_e32 v71, v77, v71
	v_mul_f32_e32 v57, v57, v74
	v_mul_f32_e32 v65, v65, v75
	v_mul_f32_e32 v59, v59, v78
	v_mul_f32_e32 v67, v67, v79
	v_mul_f32_e32 v53, v53, v80
	v_mul_f32_e32 v69, v69, v81
	v_mul_f32_e32 v55, v54, v55
	v_mul_f32_e32 v71, v76, v71
	v_mul_f32_e32 v56, v56, v57
	v_mul_f32_e32 v57, v64, v65
	v_mul_f32_e32 v58, v58, v59
	v_mul_f32_e32 v59, v66, v67
	v_mul_f32_e32 v64, v52, v53
	v_mul_f32_e32 v65, v68, v69
	v_cvt_pk_bf16_f32 v52, v71, v56
	v_cvt_pk_bf16_f32 v53, v57, v58
	v_cvt_pk_bf16_f32 v54, v59, v64
	v_cvt_pk_bf16_f32 v55, v65, v55
	global_store_dwordx4 v[62:63], v[52:55], off
	v_mov_b32_e32 v73, v40
	v_mov_b32_e32 v40, v49
	v_mov_b32_e32 v49, v42
	v_mov_b32_e32 v42, v51
	v_mov_b32_e32 v51, v36
	v_mov_b32_e32 v72, v48
	v_mov_b32_e32 v48, v50
	v_mov_b32_e32 v50, v44
	v_mov_b32_e32 v44, v46
	s_waitcnt vmcnt(9)
	v_mov_b64_e32 v[52:53], v[180:181]
	v_mov_b64_e32 v[54:55], v[182:183]
	v_add_u32_e32 v158, 0xb000, v157
	v_lshl_add_u64 v[160:161], v[158:159], 0, v[204:205]
	global_load_dwordx4 v[180:183], v[160:161], off
	v_mov_b32_e32 v74, v53
	v_mov_b32_e32 v75, v54
	v_mov_b32_e32 v53, v55
	s_waitcnt vmcnt(9)
	v_mov_b64_e32 v[56:57], v[184:185]
	v_mov_b64_e32 v[58:59], v[186:187]
	global_load_dwordx4 v[184:187], v[160:161], off offset:16
	v_mov_b32_e32 v54, v57
	v_mov_b32_e32 v55, v58
	v_mov_b32_e32 v57, v59
	v_pk_add_f32 v[52:53], v[74:75], v[52:53]
	v_pk_add_f32 v[54:55], v[54:55], v[56:57]
	v_add_f32_e32 v36, v52, v53
	v_pk_add_f32 v[52:53], v[54:55], v[54:55] op_sel:[0,1] op_sel_hi:[1,0]
	s_waitcnt vmcnt(9)
	v_mov_b64_e32 v[62:63], v[188:189]
	v_mov_b64_e32 v[64:65], v[190:191]
	global_load_dwordx4 v[188:191], v[160:161], off offset:32
	v_add_f32_e32 v58, v62, v63
	v_add_f32_e32 v62, v64, v65
	s_waitcnt vmcnt(9)
	v_mov_b64_e32 v[66:67], v[192:193]
	v_mov_b64_e32 v[68:69], v[194:195]
	global_load_dwordx4 v[192:195], v[160:161], off offset:48
	v_mov_b32_e32 v65, v66
	v_mov_b32_e32 v59, v68
	v_mov_b32_e32 v63, v69
	v_add_f32_e32 v64, 0, v36
	v_mov_b32_e32 v53, v67
	v_pk_add_f32 v[56:57], v[58:59], v[62:63]
	v_pk_add_f32 v[52:53], v[64:65], v[52:53]
	v_mov_b32_e32 v36, v45
	v_pk_add_f32 v[52:53], v[52:53], v[56:57]
	v_mov_b32_e32 v45, v38
	v_add_f32_e32 v52, v52, v53
	ds_bpermute_b32 v53, v1, v52
	v_mov_b32_e32 v38, v47
	v_mad_i64_i32 v[46:47], s[8:9], v70, s68, v[60:61]
	v_lshl_add_u64 v[46:47], v[46:47], 0, v[2:3]
	s_waitcnt lgkmcnt(0)
	v_add_f32_e32 v54, v52, v53
	ds_bpermute_b32 v55, v128, v54
	v_add_u32_e32 v52, 0xa0, v132
	v_ashrrev_i32_e32 v53, 31, v52
	s_waitcnt lgkmcnt(0)
	v_add_f32_e32 v54, v54, v55
	v_fmamk_f32 v54, v54, 0x3a000000, v226
	v_mul_f32_e32 v55, 0x4b800000, v54
	v_cmp_gt_f32_e32 vcc, s67, v54
	s_nop 1
	v_cndmask_b32_e32 v54, v54, v55, vcc
	v_rsq_f32_e32 v56, v54
	v_lshlrev_b64 v[54:55], 8, v[52:53]
	v_lshl_add_u64 v[54:55], v[204:205], 0, v[54:55]
	v_mul_f32_e32 v53, 0x45800000, v56
	v_cndmask_b32_e32 v56, v56, v53, vcc
	v_pk_mul_f32 v[38:39], v[38:39], v[56:57] op_sel_hi:[1,0]
	v_pk_mul_f32 v[58:59], v[72:73], v[56:57] op_sel_hi:[1,0]
	v_pk_mul_f32 v[40:41], v[40:41], v[56:57] op_sel_hi:[1,0]
	v_pk_mul_f32 v[48:49], v[48:49], v[56:57] op_sel_hi:[1,0]
	v_pk_mul_f32 v[42:43], v[42:43], v[56:57] op_sel_hi:[1,0]
	v_pk_mul_f32 v[50:51], v[50:51], v[56:57] op_sel_hi:[1,0]
	v_pk_mul_f32 v[36:37], v[36:37], v[56:57] op_sel_hi:[1,0]
	v_pk_mul_f32 v[44:45], v[44:45], v[56:57] op_sel_hi:[1,0]
	v_mul_f32_e32 v66, 0xbfb8aa3b, v39
	v_mul_f32_e32 v53, 0xbfb8aa3b, v59
	v_mul_f32_e32 v56, 0xbfb8aa3b, v41
	v_mul_f32_e32 v57, 0xbfb8aa3b, v49
	v_mul_f32_e32 v62, 0xbfb8aa3b, v43
	v_mul_f32_e32 v63, 0xbfb8aa3b, v51
	v_mul_f32_e32 v64, 0xbfb8aa3b, v37
	v_mul_f32_e32 v65, 0xbfb8aa3b, v45
	v_exp_f32_e32 v66, v66
	v_exp_f32_e32 v53, v53
	v_exp_f32_e32 v56, v56
	v_exp_f32_e32 v57, v57
	v_exp_f32_e32 v62, v62
	v_exp_f32_e32 v63, v63
	v_exp_f32_e32 v64, v64
	v_exp_f32_e32 v65, v65
	v_add_f32_e32 v66, 1.0, v66
	v_add_f32_e32 v53, 1.0, v53
	v_add_f32_e32 v56, 1.0, v56
	v_add_f32_e32 v57, 1.0, v57
	v_add_f32_e32 v62, 1.0, v62
	v_add_f32_e32 v63, 1.0, v63
	v_add_f32_e32 v64, 1.0, v64
	v_add_f32_e32 v65, 1.0, v65
	v_rcp_f32_e32 v66, v66
	v_rcp_f32_e32 v53, v53
	v_rcp_f32_e32 v56, v56
	v_rcp_f32_e32 v57, v57
	v_rcp_f32_e32 v62, v62
	v_rcp_f32_e32 v63, v63
	v_rcp_f32_e32 v64, v64
	v_rcp_f32_e32 v65, v65
	v_mul_f32_e32 v39, v39, v66
	v_mul_f32_e32 v53, v59, v53
	v_mul_f32_e32 v41, v41, v56
	v_mul_f32_e32 v49, v49, v57
	v_mul_f32_e32 v43, v43, v62
	v_mul_f32_e32 v51, v51, v63
	v_mul_f32_e32 v37, v37, v64
	v_mul_f32_e32 v45, v45, v65
	v_mul_f32_e32 v39, v38, v39
	v_mul_f32_e32 v53, v58, v53
	v_mul_f32_e32 v40, v40, v41
	v_mul_f32_e32 v41, v48, v49
	v_mul_f32_e32 v42, v42, v43
	v_mul_f32_e32 v43, v50, v51
	v_mul_f32_e32 v48, v36, v37
	v_mul_f32_e32 v44, v44, v45
	v_cvt_pk_bf16_f32 v36, v53, v40
	v_cvt_pk_bf16_f32 v37, v41, v42
	v_cvt_pk_bf16_f32 v38, v43, v48
	v_cvt_pk_bf16_f32 v39, v44, v39
	global_store_dwordx4 v[46:47], v[36:39], off
	v_mov_b32_e32 v55, v24
	v_mov_b32_e32 v24, v33
	v_mov_b32_e32 v33, v26
	v_mov_b32_e32 v26, v35
	v_mov_b32_e32 v35, v20
	v_mov_b32_e32 v54, v32
	v_mov_b32_e32 v32, v34
	v_mov_b32_e32 v34, v28
	v_mov_b32_e32 v28, v30
	s_waitcnt vmcnt(9)
	v_mov_b64_e32 v[36:37], v[164:165]
	v_mov_b64_e32 v[38:39], v[166:167]
	v_mov_b32_e32 v56, v37
	v_mov_b32_e32 v57, v38
	v_mov_b32_e32 v37, v39
	s_waitcnt vmcnt(8)
	v_mov_b64_e32 v[40:41], v[168:169]
	v_mov_b64_e32 v[42:43], v[170:171]
	v_mov_b32_e32 v38, v41
	v_mov_b32_e32 v39, v42
	v_mov_b32_e32 v41, v43
	v_pk_add_f32 v[36:37], v[56:57], v[36:37]
	v_pk_add_f32 v[38:39], v[38:39], v[40:41]
	v_add_f32_e32 v20, v36, v37
	v_pk_add_f32 v[36:37], v[38:39], v[38:39] op_sel:[0,1] op_sel_hi:[1,0]
	s_waitcnt vmcnt(7)
	v_mov_b64_e32 v[44:45], v[172:173]
	v_mov_b64_e32 v[46:47], v[174:175]
	v_add_f32_e32 v42, v44, v45
	v_add_f32_e32 v44, v46, v47
	s_waitcnt vmcnt(6)
	v_mov_b64_e32 v[48:49], v[176:177]
	v_mov_b64_e32 v[50:51], v[178:179]
	v_mov_b32_e32 v47, v48
	v_mov_b32_e32 v43, v50
	v_mov_b32_e32 v45, v51
	v_add_f32_e32 v46, 0, v20
	v_mov_b32_e32 v37, v49
	v_pk_add_f32 v[40:41], v[42:43], v[44:45]
	v_pk_add_f32 v[36:37], v[46:47], v[36:37]
	v_mov_b32_e32 v20, v29
	v_pk_add_f32 v[36:37], v[36:37], v[40:41]
	v_mov_b32_e32 v29, v22
	v_add_f32_e32 v36, v36, v37
	ds_bpermute_b32 v37, v1, v36
	v_mov_b32_e32 v22, v31
	v_mad_i64_i32 v[30:31], s[8:9], v52, s68, v[60:61]
	v_lshl_add_u64 v[30:31], v[30:31], 0, v[2:3]
	s_waitcnt lgkmcnt(0)
	v_add_f32_e32 v38, v36, v37
	ds_bpermute_b32 v39, v128, v38
	v_add_u32_e32 v36, 0xb0, v132
	v_ashrrev_i32_e32 v37, 31, v36
	s_waitcnt lgkmcnt(0)
	v_add_f32_e32 v38, v38, v39
	v_fmamk_f32 v38, v38, 0x3a000000, v226
	v_mul_f32_e32 v39, 0x4b800000, v38
	v_cmp_gt_f32_e32 vcc, s67, v38
	s_nop 1
	v_cndmask_b32_e32 v38, v38, v39, vcc
	v_rsq_f32_e32 v40, v38
	v_lshlrev_b64 v[38:39], 8, v[36:37]
	v_lshl_add_u64 v[38:39], v[204:205], 0, v[38:39]
	v_mul_f32_e32 v37, 0x45800000, v40
	v_cndmask_b32_e32 v40, v40, v37, vcc
	v_pk_mul_f32 v[22:23], v[22:23], v[40:41] op_sel_hi:[1,0]
	v_pk_mul_f32 v[42:43], v[54:55], v[40:41] op_sel_hi:[1,0]
	v_pk_mul_f32 v[24:25], v[24:25], v[40:41] op_sel_hi:[1,0]
	v_pk_mul_f32 v[32:33], v[32:33], v[40:41] op_sel_hi:[1,0]
	v_pk_mul_f32 v[26:27], v[26:27], v[40:41] op_sel_hi:[1,0]
	v_pk_mul_f32 v[34:35], v[34:35], v[40:41] op_sel_hi:[1,0]
	v_pk_mul_f32 v[20:21], v[20:21], v[40:41] op_sel_hi:[1,0]
	v_pk_mul_f32 v[28:29], v[28:29], v[40:41] op_sel_hi:[1,0]
	v_mul_f32_e32 v48, 0xbfb8aa3b, v23
	v_mul_f32_e32 v37, 0xbfb8aa3b, v43
	v_mul_f32_e32 v40, 0xbfb8aa3b, v25
	v_mul_f32_e32 v41, 0xbfb8aa3b, v33
	v_mul_f32_e32 v44, 0xbfb8aa3b, v27
	v_mul_f32_e32 v45, 0xbfb8aa3b, v35
	v_mul_f32_e32 v46, 0xbfb8aa3b, v21
	v_mul_f32_e32 v47, 0xbfb8aa3b, v29
	v_exp_f32_e32 v48, v48
	v_exp_f32_e32 v37, v37
	v_exp_f32_e32 v40, v40
	v_exp_f32_e32 v41, v41
	v_exp_f32_e32 v44, v44
	v_exp_f32_e32 v45, v45
	v_exp_f32_e32 v46, v46
	v_exp_f32_e32 v47, v47
	v_add_f32_e32 v48, 1.0, v48
	v_add_f32_e32 v37, 1.0, v37
	v_add_f32_e32 v40, 1.0, v40
	v_add_f32_e32 v41, 1.0, v41
	v_add_f32_e32 v44, 1.0, v44
	v_add_f32_e32 v45, 1.0, v45
	v_add_f32_e32 v46, 1.0, v46
	v_add_f32_e32 v47, 1.0, v47
	v_rcp_f32_e32 v48, v48
	v_rcp_f32_e32 v37, v37
	v_rcp_f32_e32 v40, v40
	v_rcp_f32_e32 v41, v41
	v_rcp_f32_e32 v44, v44
	v_rcp_f32_e32 v45, v45
	v_rcp_f32_e32 v46, v46
	v_rcp_f32_e32 v47, v47
	v_mul_f32_e32 v23, v23, v48
	v_mul_f32_e32 v37, v43, v37
	v_mul_f32_e32 v25, v25, v40
	v_mul_f32_e32 v33, v33, v41
	v_mul_f32_e32 v27, v27, v44
	v_mul_f32_e32 v35, v35, v45
	v_mul_f32_e32 v21, v21, v46
	v_mul_f32_e32 v29, v29, v47
	v_mul_f32_e32 v23, v22, v23
	v_mul_f32_e32 v37, v42, v37
	v_mul_f32_e32 v24, v24, v25
	v_mul_f32_e32 v25, v32, v33
	v_mul_f32_e32 v26, v26, v27
	v_mul_f32_e32 v27, v34, v35
	v_mul_f32_e32 v32, v20, v21
	v_mul_f32_e32 v28, v28, v29
	v_cvt_pk_bf16_f32 v20, v37, v24
	v_cvt_pk_bf16_f32 v21, v25, v26
	v_cvt_pk_bf16_f32 v22, v27, v32
	v_cvt_pk_bf16_f32 v23, v28, v23
	global_store_dwordx4 v[30:31], v[20:23], off
	v_mov_b32_e32 v38, v16
	v_mov_b32_e32 v39, v8
	v_mov_b32_e32 v8, v17
	s_waitcnt vmcnt(5)
	v_mov_b64_e32 v[20:21], v[180:181]
	v_mov_b64_e32 v[22:23], v[182:183]
	v_mov_b32_e32 v16, v21
	v_mov_b32_e32 v17, v22
	v_mov_b32_e32 v21, v23
	s_waitcnt vmcnt(4)
	v_mov_b64_e32 v[24:25], v[184:185]
	v_mov_b64_e32 v[26:27], v[186:187]
	v_mov_b32_e32 v22, v25
	v_mov_b32_e32 v23, v26
	v_mov_b32_e32 v25, v27
	v_pk_add_f32 v[16:17], v[16:17], v[20:21]
	v_pk_add_f32 v[20:21], v[22:23], v[24:25]
	v_add_f32_e32 v24, v16, v17
	v_pk_add_f32 v[16:17], v[20:21], v[20:21] op_sel:[0,1] op_sel_hi:[1,0]
	s_waitcnt vmcnt(3)
	v_mov_b64_e32 v[28:29], v[188:189]
	v_mov_b64_e32 v[30:31], v[190:191]
	v_add_f32_e32 v26, v28, v29
	v_add_f32_e32 v28, v30, v31
	s_waitcnt vmcnt(2)
	v_mov_b64_e32 v[32:33], v[192:193]
	v_mov_b64_e32 v[34:35], v[194:195]
	v_mov_b32_e32 v31, v32
	v_mov_b32_e32 v27, v34
	v_mov_b32_e32 v29, v35
	v_add_f32_e32 v30, 0, v24
	v_mov_b32_e32 v17, v33
	v_pk_add_f32 v[22:23], v[26:27], v[28:29]
	v_pk_add_f32 v[16:17], v[30:31], v[16:17]
	s_nop 0
	v_pk_add_f32 v[16:17], v[16:17], v[22:23]
	s_nop 0
	v_add_f32_e32 v20, v16, v17
	ds_bpermute_b32 v1, v1, v20
	v_mov_b32_e32 v17, v10
	v_mov_b32_e32 v10, v19
	v_mov_b32_e32 v19, v4
	v_mov_b32_e32 v4, v13
	s_waitcnt lgkmcnt(0)
	v_add_f32_e32 v1, v20, v1
	ds_bpermute_b32 v20, v128, v1
	v_mov_b32_e32 v13, v6
	v_mov_b32_e32 v16, v18
	v_mov_b32_e32 v18, v12
	v_mov_b32_e32 v12, v14
	s_waitcnt lgkmcnt(0)
	v_add_f32_e32 v1, v1, v20
	v_fmamk_f32 v1, v1, 0x3a000000, v226
	v_mul_f32_e32 v6, 0x4b800000, v1
	v_cmp_gt_f32_e32 vcc, s67, v1
	s_nop 1
	v_cndmask_b32_e32 v1, v1, v6, vcc
	v_rsq_f32_e32 v1, v1
	v_mov_b32_e32 v6, v15
	v_mad_i64_i32 v[14:15], s[8:9], v36, s68, v[60:61]
	v_mul_f32_e32 v20, 0x45800000, v1
	v_cndmask_b32_e32 v20, v1, v20, vcc
	v_pk_mul_f32 v[6:7], v[6:7], v[20:21] op_sel_hi:[1,0]
	v_pk_mul_f32 v[22:23], v[38:39], v[20:21] op_sel_hi:[1,0]
	v_pk_mul_f32 v[8:9], v[8:9], v[20:21] op_sel_hi:[1,0]
	v_pk_mul_f32 v[16:17], v[16:17], v[20:21] op_sel_hi:[1,0]
	v_pk_mul_f32 v[10:11], v[10:11], v[20:21] op_sel_hi:[1,0]
	v_pk_mul_f32 v[18:19], v[18:19], v[20:21] op_sel_hi:[1,0]
	v_pk_mul_f32 v[4:5], v[4:5], v[20:21] op_sel_hi:[1,0]
	v_pk_mul_f32 v[12:13], v[12:13], v[20:21] op_sel_hi:[1,0]
	v_mul_f32_e32 v28, 0xbfb8aa3b, v7
	v_mul_f32_e32 v1, 0xbfb8aa3b, v23
	v_mul_f32_e32 v20, 0xbfb8aa3b, v9
	v_mul_f32_e32 v21, 0xbfb8aa3b, v17
	v_mul_f32_e32 v24, 0xbfb8aa3b, v11
	v_mul_f32_e32 v25, 0xbfb8aa3b, v19
	v_mul_f32_e32 v26, 0xbfb8aa3b, v5
	v_mul_f32_e32 v27, 0xbfb8aa3b, v13
	v_exp_f32_e32 v28, v28
	v_exp_f32_e32 v1, v1
	v_exp_f32_e32 v20, v20
	v_exp_f32_e32 v21, v21
	v_exp_f32_e32 v24, v24
	v_exp_f32_e32 v25, v25
	v_exp_f32_e32 v26, v26
	v_exp_f32_e32 v27, v27
	v_add_f32_e32 v28, 1.0, v28
	v_add_f32_e32 v1, 1.0, v1
	v_add_f32_e32 v20, 1.0, v20
	v_add_f32_e32 v21, 1.0, v21
	v_add_f32_e32 v24, 1.0, v24
	v_add_f32_e32 v25, 1.0, v25
	v_add_f32_e32 v26, 1.0, v26
	v_add_f32_e32 v27, 1.0, v27
	v_rcp_f32_e32 v28, v28
	v_rcp_f32_e32 v1, v1
	v_rcp_f32_e32 v20, v20
	v_rcp_f32_e32 v21, v21
	v_rcp_f32_e32 v24, v24
	v_rcp_f32_e32 v25, v25
	v_rcp_f32_e32 v26, v26
	v_rcp_f32_e32 v27, v27
	v_mul_f32_e32 v7, v7, v28
	v_mul_f32_e32 v1, v23, v1
	v_mul_f32_e32 v9, v9, v20
	v_mul_f32_e32 v17, v17, v21
	v_mul_f32_e32 v11, v11, v24
	v_mul_f32_e32 v19, v19, v25
	v_mul_f32_e32 v5, v5, v26
	v_mul_f32_e32 v13, v13, v27
	v_mul_f32_e32 v7, v6, v7
	v_lshl_add_u64 v[2:3], v[14:15], 0, v[2:3]
	v_mul_f32_e32 v1, v22, v1
	v_mul_f32_e32 v8, v8, v9
	v_mul_f32_e32 v9, v16, v17
	v_mul_f32_e32 v10, v10, v11
	v_mul_f32_e32 v11, v18, v19
	v_mul_f32_e32 v16, v4, v5
	v_mul_f32_e32 v12, v12, v13
	v_cvt_pk_bf16_f32 v4, v1, v8
	v_cvt_pk_bf16_f32 v5, v9, v10
	v_cvt_pk_bf16_f32 v6, v11, v16
	v_cvt_pk_bf16_f32 v7, v12, v7
	global_store_dwordx4 v[2:3], v[4:7], off
	s_andn2_b64 vcc, exec, s[24:25]
	s_mov_b64 s[8:9], -1
	s_cbranch_vccnz .LBB0_1036
